# adds bpermute-coalesced MIX stores in the GLU epilogue (4 adjacent lanes write 64 contiguous bytes of a row)
# baseline (speedup 1.0000x reference)
; __device__ __forceinline__ unsigned cvt_pk_bf16(float lo, float hi) { const cvt_f32x2_t v = {lo, hi}; const cvt_bf16x2_t b = __builtin_convertvector(v, cvt_bf16x2_t); return __builtin_bit_cast(unsigned, b); }
; __device__ __forceinline__ float bf_lo(unsigned u) { return __uint_as_float(u << 16); }
; __device__ __forceinline__ float bf_hi(unsigned u) { return __uint_as_float(u & 0xffff0000u); }
;     __device__ __forceinline__ void operator()(const f32x4 (&acc)[2][2][4][2], const Unit& u, int wr, int wc, int fr, int fq) const {
;         const int col0 = u.pn * 256 + wc * 32 + 8 * fq;
;         f32x4 gv[2][2];
; #pragma unroll
;         for (int bj = 0; bj < 2; ++bj)
; #pragma unroll
;             for (int n = 0; n < 2; ++n) gv[bj][n] = *(const f32x4*)(gs + col0 + 128 * bj + 4 * n);
; #pragma unroll
;         for (int ai = 0; ai < 2; ++ai) {
;             u32x4 zpre[4][2];
; #pragma unroll
;             for (int m = 0; m < 4; ++m)
; #pragma unroll
;                 for (int bj = 0; bj < 2; ++bj) zpre[m][bj] = *(const u32x4*)(Z + (size_t)(u.pm * 256 + ai * 128 + wr * 64 + m * 16 + fr) * SW + col0 + 128 * bj);
;             asm volatile("" ::: "memory");
; #pragma unroll
;             for (int m = 0; m < 4; ++m) {
;                 const int row = u.pm * 256 + ai * 128 + wr * 64 + m * 16 + fr;
;                 float ss = 0.f;
; #pragma unroll
;                 for (int bj = 0; bj < 2; ++bj) {
;                     const u32x4 zz = zpre[m][bj];
;                     const f32x4 a = acc[ai][bj][m][0], c = acc[ai][bj][m][1];
;                     f32x4 o0, o1;
;                     o0[0] = bf_lo(zz.x) * sigmoidf_(a[0]); o0[1] = bf_hi(zz.x) * sigmoidf_(a[1]); o0[2] = bf_lo(zz.y) * sigmoidf_(a[2]); o0[3] = bf_hi(zz.y) * sigmoidf_(a[3]);
;                     o1[0] = bf_lo(zz.z) * sigmoidf_(c[0]); o1[1] = bf_hi(zz.z) * sigmoidf_(c[1]); o1[2] = bf_lo(zz.w) * sigmoidf_(c[2]); o1[3] = bf_hi(zz.w) * sigmoidf_(c[3]);
;                     ss += sq4(o0) + sq4(o1);
;                     o0 = o0 * gv[bj][0]; o1 = o1 * gv[bj][1];
;                     u32x4 w; w.x = cvt_pk_bf16(o0[0], o0[1]); w.y = cvt_pk_bf16(o0[2], o0[3]); w.z = cvt_pk_bf16(o1[0], o1[1]); w.w = cvt_pk_bf16(o1[2], o1[3]);
;                     *(u32x4*)(MIX + (size_t)row * DM + AW + col0 + 128 * bj) = w;
.LBB0_391:
	v_and_b32_e32 v226, 3, v242
	v_lshrrev_b32_e32 v224, 2, v242
	v_lshl_add_u32 v225, v226, 4, v224
	v_sub_u32_e32 v224, v224, v182
	v_sub_u32_e32 v226, v226, v183
	v_lshlrev_b32_e32 v224, 11, v224
	v_lshl_add_u32 v224, v226, 4, v224
	v_lshlrev_b32_e32 v226, 2, v225
	v_ashrrev_i32_e32 v225, 31, v224
	s_lshl_b32 s8, s81, 8
	v_mov_b32_e32 v72, v182
	v_mov_b32_e32 v140, v183
	s_or_b32 s8, s8, s65
	v_and_b32_e32 v142, 64, v242
	v_lshl_add_u32 v170, v140, 3, s8
	s_lshl_b32 s8, s84, 8
	s_add_i32 s8, s8, s64
	v_ashrrev_i32_e32 v171, 31, v170
	v_add_u32_e32 v174, s8, v72
	v_lshlrev_b64 v[198:199], 1, v[170:171]
	v_ashrrev_i32_e32 v175, 31, v174
	v_lshl_add_u64 v[172:173], s[16:17], 0, v[198:199]
	v_lshlrev_b64 v[72:73], 10, v[174:175]
	v_lshl_add_u64 v[136:137], v[172:173], 0, v[72:73]
	global_load_dwordx4 v[188:191], v[136:137], off
	v_lshl_add_u64 v[138:139], v[170:171], 2, s[20:21]
	global_load_dwordx4 v[72:75], v[138:139], off offset:16
	global_load_dwordx4 v[76:79], v[138:139], off
	global_load_dwordx4 v[194:197], v[136:137], off offset:256
	v_xor_b32_e32 v141, 16, v242
	v_add_u32_e32 v142, 64, v142
	v_xor_b32_e32 v143, 32, v242
	v_mul_f32_e32 v64, 0xbfb8aa3b, v64
	v_mul_f32_e32 v65, 0xbfb8aa3b, v65
	v_mul_f32_e32 v66, 0xbfb8aa3b, v66
	v_mul_f32_e32 v67, 0xbfb8aa3b, v67
	v_mul_f32_e32 v60, 0xbfb8aa3b, v60
	v_mul_f32_e32 v61, 0xbfb8aa3b, v61
	v_cmp_lt_i32_e64 s[44:45], v141, v142
	v_exp_f32_e32 v144, v64
	v_exp_f32_e32 v145, v65
	v_exp_f32_e32 v146, v66
	v_exp_f32_e32 v147, v67
	v_exp_f32_e32 v148, v60
	v_exp_f32_e32 v149, v61
	v_cndmask_b32_e64 v60, v242, v141, s[44:45]
	v_cmp_lt_i32_e64 s[44:45], v143, v142
	v_mul_f32_e32 v62, 0xbfb8aa3b, v62
	v_mul_f32_e32 v63, 0xbfb8aa3b, v63
	v_cndmask_b32_e64 v61, v242, v143, s[44:45]
	v_add_u32_e32 v180, 16, v174
	v_add_u32_e32 v178, 32, v174
	v_exp_f32_e32 v207, v62
	v_exp_f32_e32 v211, v63
	v_add_u32_e32 v176, 48, v174
	v_lshlrev_b32_e32 v187, 2, v60
	v_lshlrev_b32_e32 v186, 2, v61
	v_ashrrev_i32_e32 v181, 31, v180
	v_ashrrev_i32_e32 v179, 31, v178
	global_load_dwordx4 v[60:63], v[138:139], off offset:528
	global_load_dwordx4 v[64:67], v[138:139], off offset:512
	v_ashrrev_i32_e32 v177, 31, v176
	v_lshlrev_b64 v[136:137], 10, v[180:181]
	v_lshlrev_b64 v[138:139], 10, v[178:179]
	v_cmp_eq_u32_e32 vcc, 0, v140
	v_lshlrev_b64 v[140:141], 10, v[176:177]
	v_add_f32_e32 v142, 1.0, v144
	v_add_f32_e32 v143, 1.0, v145
	v_add_f32_e32 v144, 1.0, v146
	v_add_f32_e32 v145, 1.0, v147
	v_add_f32_e32 v146, 1.0, v148
	v_add_f32_e32 v147, 1.0, v149
	v_lshl_add_u64 v[136:137], v[172:173], 0, v[136:137]
	v_lshl_add_u64 v[138:139], v[172:173], 0, v[138:139]
	v_lshl_add_u64 v[202:203], v[172:173], 0, v[140:141]
	v_rcp_f32_e32 v204, v142
	v_rcp_f32_e32 v205, v143
	v_rcp_f32_e32 v212, v144
	v_rcp_f32_e32 v213, v145
	v_rcp_f32_e32 v214, v146
	v_rcp_f32_e32 v215, v147
	global_load_dwordx4 v[156:159], v[136:137], off
	global_load_dwordx4 v[152:155], v[136:137], off offset:256
	global_load_dwordx4 v[148:151], v[138:139], off
	global_load_dwordx4 v[144:147], v[138:139], off offset:256
	global_load_dwordx4 v[140:143], v[202:203], off
	s_nop 0
	global_load_dwordx4 v[136:139], v[202:203], off offset:256
	v_mul_f32_e32 v132, 0xbfb8aa3b, v132
	v_mul_f32_e32 v133, 0xbfb8aa3b, v133
	v_exp_f32_e32 v132, v132
	v_exp_f32_e32 v133, v133
	v_mul_f32_e32 v134, 0xbfb8aa3b, v134
	v_mul_f32_e32 v135, 0xbfb8aa3b, v135
	v_exp_f32_e32 v134, v134
	v_exp_f32_e32 v135, v135
	v_lshlrev_b64 v[200:201], 11, v[174:175]
	v_lshl_add_u64 v[200:201], s[38:39], 0, v[200:201]
	v_lshl_add_u64 v[198:199], v[200:201], 0, v[198:199]
	v_add_f32_e32 v132, 1.0, v132
	v_add_f32_e32 v133, 1.0, v133
	v_mul_f32_e32 v128, 0xbfb8aa3b, v128
	v_rcp_f32_e32 v132, v132
	v_rcp_f32_e32 v133, v133
	v_add_f32_e32 v134, 1.0, v134
	v_add_f32_e32 v135, 1.0, v135
	v_rcp_f32_e32 v134, v134
	v_rcp_f32_e32 v135, v135
	v_mul_f32_e32 v130, 0xbfb8aa3b, v130
	v_mul_f32_e32 v131, 0xbfb8aa3b, v131
	v_exp_f32_e32 v130, v130
	s_waitcnt vmcnt(0)
	v_lshlrev_b32_e32 v202, 16, v188
	v_and_b32_e32 v203, 0xffff0000, v188
	v_lshlrev_b32_e32 v216, 16, v190
	v_and_b32_e32 v217, 0xffff0000, v190
	v_add_f32_e32 v190, 1.0, v207
	v_pk_mul_f32 v[202:203], v[204:205], v[202:203]
	v_rcp_f32_e32 v204, v190
	v_add_f32_e32 v190, 1.0, v211
	v_rcp_f32_e32 v205, v190
	v_lshlrev_b32_e32 v188, 16, v189
	v_and_b32_e32 v189, 0xffff0000, v189
	v_lshlrev_b32_e32 v190, 16, v191
	v_and_b32_e32 v191, 0xffff0000, v191
	v_pk_mul_f32 v[188:189], v[212:213], v[188:189]
	v_pk_mul_f32 v[212:213], v[214:215], v[216:217]
	v_pk_mul_f32 v[190:191], v[204:205], v[190:191]
	v_pk_mul_f32 v[204:205], v[202:203], v[202:203]
	v_pk_mul_f32 v[214:215], v[188:189], v[188:189]
	v_pk_mul_f32 v[218:219], v[190:191], v[190:191]
	v_pk_mul_f32 v[220:221], v[78:79], v[188:189]
	v_pk_mul_f32 v[188:189], v[76:77], v[202:203]
	v_pk_mul_f32 v[202:203], v[74:75], v[190:191]
	v_pk_mul_f32 v[190:191], v[72:73], v[212:213]
	v_cvt_pk_bf16_f32 v188, v188, v189
	v_cvt_pk_bf16_f32 v189, v220, v221
	v_cvt_pk_bf16_f32 v190, v190, v191
	v_cvt_pk_bf16_f32 v191, v202, v203
	v_lshl_add_u64 v[198:199], v[224:225], 0, v[198:199]
	ds_bpermute_b32 v188, v226, v188
	ds_bpermute_b32 v189, v226, v189
	ds_bpermute_b32 v190, v226, v190
	ds_bpermute_b32 v191, v226, v191
	s_waitcnt lgkmcnt(0)
; __device__ __forceinline__ unsigned cvt_pk_bf16(float lo, float hi) { const cvt_f32x2_t v = {lo, hi}; const cvt_bf16x2_t b = __builtin_convertvector(v, cvt_bf16x2_t); return __builtin_bit_cast(unsigned, b); }
; __device__ __forceinline__ float bf_lo(unsigned u) { return __uint_as_float(u << 16); }
; __device__ __forceinline__ float bf_hi(unsigned u) { return __uint_as_float(u & 0xffff0000u); }
; __device__ __forceinline__ float sq4(f32x4 v) { return (v[0] * v[0] + v[1] * v[1]) + (v[2] * v[2] + v[3] * v[3]); }
; __device__ __forceinline__ float sigmoidf_(float x) { return __builtin_amdgcn_rcpf(1.0f + __builtin_amdgcn_exp2f(-LOG2E * x)); }
;     __device__ __forceinline__ void operator()(const f32x4 (&acc)[2][2][4][2], const Unit& u, int wr, int wc, int fr, int fq) const {
;     ...
;                 for (int bj = 0; bj < 2; ++bj) {
;                     const u32x4 zz = zpre[m][bj];
;                     const f32x4 a = acc[ai][bj][m][0], c = acc[ai][bj][m][1];
;                     f32x4 o0, o1;
;                     o0[0] = bf_lo(zz.x) * sigmoidf_(a[0]); o0[1] = bf_hi(zz.x) * sigmoidf_(a[1]); o0[2] = bf_lo(zz.y) * sigmoidf_(a[2]); o0[3] = bf_hi(zz.y) * sigmoidf_(a[3]);
;                     o1[0] = bf_lo(zz.z) * sigmoidf_(c[0]); o1[1] = bf_hi(zz.z) * sigmoidf_(c[1]); o1[2] = bf_lo(zz.w) * sigmoidf_(c[2]); o1[3] = bf_hi(zz.w) * sigmoidf_(c[3]);
;                     ss += sq4(o0) + sq4(o1);
;                     o0 = o0 * gv[bj][0]; o1 = o1 * gv[bj][1];
;                     u32x4 w; w.x = cvt_pk_bf16(o0[0], o0[1]); w.y = cvt_pk_bf16(o0[2], o0[3]); w.z = cvt_pk_bf16(o1[0], o1[1]); w.w = cvt_pk_bf16(o1[2], o1[3]);
;                     *(u32x4*)(MIX + (size_t)row * DM + AW + col0 + 128 * bj) = w;
;                 }
;                 ss += __shfl_xor(ss, 16); ss += __shfl_xor(ss, 32);
;                 if (fq == 0) stats[(size_t)row * 8 + u.pn * 4 + wc] = ss;
	global_store_dwordx4 v[198:199], v[188:191], off offset:1024
	v_exp_f32_e32 v131, v131
	v_add_f32_e32 v130, 1.0, v130
	v_exp_f32_e32 v190, v128
	v_mul_f32_e32 v128, 0xbfb8aa3b, v129
	v_exp_f32_e32 v191, v128
	v_lshlrev_b32_e32 v188, 16, v194
	v_and_b32_e32 v189, 0xffff0000, v194
	v_pk_mul_f32 v[132:133], v[132:133], v[188:189]
	v_lshlrev_b32_e32 v188, 16, v195
	v_and_b32_e32 v189, 0xffff0000, v195
	v_pk_mul_f32 v[128:129], v[134:135], v[188:189]
	v_add_f32_e32 v134, 1.0, v190
	v_add_f32_e32 v135, 1.0, v191
	v_rcp_f32_e32 v134, v134
	v_rcp_f32_e32 v135, v135
	v_add_f32_e32 v131, 1.0, v131
	v_rcp_f32_e32 v130, v130
	v_rcp_f32_e32 v131, v131
	v_lshlrev_b32_e32 v188, 16, v196
	v_and_b32_e32 v189, 0xffff0000, v196
	v_pk_mul_f32 v[134:135], v[134:135], v[188:189]
	v_lshlrev_b32_e32 v188, 16, v197
	v_and_b32_e32 v189, 0xffff0000, v197
	v_pk_mul_f32 v[130:131], v[130:131], v[188:189]
	v_pk_mul_f32 v[188:189], v[132:133], v[132:133]
	v_pk_mul_f32 v[190:191], v[128:129], v[128:129]
	v_pk_mul_f32 v[216:217], v[212:213], v[212:213]
	v_add_f32_e32 v190, v190, v191
	v_add_f32_e32 v188, v188, v189
	v_pk_mul_f32 v[194:195], v[134:135], v[134:135]
	v_pk_mul_f32 v[196:197], v[130:131], v[130:131]
	v_add_f32_e32 v188, v188, v190
	v_add_f32_e32 v189, v218, v219
	v_add_f32_e32 v190, v216, v217
	v_add_f32_e32 v196, v196, v197
	v_add_f32_e32 v194, v194, v195
	v_add_f32_e32 v189, v190, v189
	v_add_f32_e32 v190, v214, v215
	v_add_f32_e32 v191, v204, v205
	v_add_f32_e32 v194, v194, v196
	v_add_f32_e32 v190, v191, v190
	v_add_f32_e32 v188, v188, v194
	v_add_f32_e32 v189, v190, v189
	v_add_f32_e32 v194, v189, v188
	ds_bpermute_b32 v195, v187, v194
	v_pk_mul_f32 v[188:189], v[66:67], v[128:129]
	v_pk_mul_f32 v[128:129], v[64:65], v[132:133]
	v_pk_mul_f32 v[190:191], v[62:63], v[130:131]
	v_cvt_pk_bf16_f32 v130, v128, v129
	s_waitcnt lgkmcnt(0)
	v_add_f32_e32 v128, v194, v195
	ds_bpermute_b32 v129, v186, v128
	v_pk_mul_f32 v[132:133], v[60:61], v[134:135]
	s_lshl_b32 s92, s81, 2
	v_cvt_pk_bf16_f32 v131, v188, v189
	v_cvt_pk_bf16_f32 v132, v132, v133
	v_cvt_pk_bf16_f32 v133, v190, v191
	ds_bpermute_b32 v130, v226, v130
	ds_bpermute_b32 v131, v226, v131
	ds_bpermute_b32 v132, v226, v132
	ds_bpermute_b32 v133, v226, v133
	s_waitcnt lgkmcnt(0)
	global_store_dwordx4 v[198:199], v[130:133], off offset:1280
	s_and_saveexec_b64 s[44:45], vcc
	s_load_dword s85, s[0:1], 0xd8
	s_mov_b32 s90, 0xfffe8000
	s_mov_b32 s91, 0xffff4000
	s_cbranch_execz .LBB0_393
	v_lshlrev_b64 v[130:131], 5, v[174:175]
	v_lshl_add_u64 v[130:131], s[22:23], 0, v[130:131]
	v_lshl_add_u64 v[130:131], s[92:93], 2, v[130:131]
	s_lshl_b32 s42, s63, 2
	s_mov_b32 s43, s93
	v_lshl_add_u64 v[130:131], v[130:131], 0, s[42:43]
	s_waitcnt lgkmcnt(0)
	v_add_f32_e32 v128, v128, v129
	global_store_dword v[130:131], v128, off
.LBB0_393:
	s_or_b64 exec, exec, s[44:45]
	v_mul_f32_e32 v124, 0xbfb8aa3b, v124
	v_exp_f32_e32 v128, v124
	v_mul_f32_e32 v124, 0xbfb8aa3b, v125
	s_waitcnt lgkmcnt(0)
	v_exp_f32_e32 v129, v124
	v_mul_f32_e32 v126, 0xbfb8aa3b, v126
	v_add_f32_e32 v128, 1.0, v128
	v_exp_f32_e32 v132, v126
	v_add_f32_e32 v129, 1.0, v129
	v_mul_f32_e32 v126, 0xbfb8aa3b, v127
	v_rcp_f32_e32 v128, v128
	v_rcp_f32_e32 v129, v129
	v_exp_f32_e32 v133, v126
	v_lshlrev_b32_e32 v130, 16, v156
	v_and_b32_e32 v131, 0xffff0000, v156
	v_mul_f32_e32 v120, 0xbfb8aa3b, v120
	v_pk_mul_f32 v[126:127], v[128:129], v[130:131]
	v_add_f32_e32 v128, 1.0, v132
	v_add_f32_e32 v129, 1.0, v133
	v_exp_f32_e32 v132, v120
	v_mul_f32_e32 v120, 0xbfb8aa3b, v121
	v_rcp_f32_e32 v128, v128
	v_rcp_f32_e32 v129, v129
	v_exp_f32_e32 v133, v120
	v_mul_f32_e32 v122, 0xbfb8aa3b, v122
	v_mul_f32_e32 v123, 0xbfb8aa3b, v123
	v_exp_f32_e32 v122, v122
	v_exp_f32_e32 v123, v123
	v_lshlrev_b32_e32 v130, 16, v157
	v_and_b32_e32 v131, 0xffff0000, v157
	v_pk_mul_f32 v[120:121], v[128:129], v[130:131]
	v_add_f32_e32 v128, 1.0, v132
	v_add_f32_e32 v129, 1.0, v133
	v_rcp_f32_e32 v128, v128
	v_rcp_f32_e32 v129, v129
	v_add_f32_e32 v122, 1.0, v122
	v_add_f32_e32 v123, 1.0, v123
	v_rcp_f32_e32 v122, v122
	v_rcp_f32_e32 v123, v123
	v_mul_f32_e32 v116, 0xbfb8aa3b, v116
	v_mul_f32_e32 v117, 0xbfb8aa3b, v117
	v_lshlrev_b32_e32 v130, 16, v158
	v_and_b32_e32 v131, 0xffff0000, v158
	v_exp_f32_e32 v116, v116
	v_exp_f32_e32 v117, v117
	v_mul_f32_e32 v118, 0xbfb8aa3b, v118
	v_mul_f32_e32 v119, 0xbfb8aa3b, v119
	v_pk_mul_f32 v[128:129], v[128:129], v[130:131]
	v_lshlrev_b32_e32 v130, 16, v159
	v_and_b32_e32 v131, 0xffff0000, v159
	v_exp_f32_e32 v118, v118
	v_exp_f32_e32 v119, v119
	v_lshlrev_b64 v[124:125], 11, v[180:181]
	v_pk_mul_f32 v[122:123], v[122:123], v[130:131]
	v_pk_mul_f32 v[130:131], v[126:127], v[126:127]
	v_pk_mul_f32 v[132:133], v[120:121], v[120:121]
	v_pk_mul_f32 v[156:157], v[122:123], v[122:123]
	v_pk_mul_f32 v[158:159], v[78:79], v[120:121]
	v_pk_mul_f32 v[120:121], v[76:77], v[126:127]
	v_pk_mul_f32 v[126:127], v[74:75], v[122:123]
	v_pk_mul_f32 v[122:123], v[72:73], v[128:129]
	v_lshl_add_u64 v[124:125], s[38:39], 0, v[124:125]
	v_cvt_pk_bf16_f32 v120, v120, v121
	v_cvt_pk_bf16_f32 v121, v158, v159
	v_cvt_pk_bf16_f32 v122, v122, v123
	v_cvt_pk_bf16_f32 v123, v126, v127
	v_lshl_add_u64 v[124:125], v[170:171], 1, v[124:125]
	v_add_f32_e32 v116, 1.0, v116
	v_add_f32_e32 v117, 1.0, v117
	v_mul_f32_e32 v112, 0xbfb8aa3b, v112
	v_lshl_add_u64 v[124:125], v[224:225], 0, v[124:125]
	ds_bpermute_b32 v120, v226, v120
	ds_bpermute_b32 v121, v226, v121
	ds_bpermute_b32 v122, v226, v122
	ds_bpermute_b32 v123, v226, v123
	s_waitcnt lgkmcnt(0)
; __device__ __forceinline__ unsigned cvt_pk_bf16(float lo, float hi) { const cvt_f32x2_t v = {lo, hi}; const cvt_bf16x2_t b = __builtin_convertvector(v, cvt_bf16x2_t); return __builtin_bit_cast(unsigned, b); }
; __device__ __forceinline__ float bf_lo(unsigned u) { return __uint_as_float(u << 16); }
; __device__ __forceinline__ float bf_hi(unsigned u) { return __uint_as_float(u & 0xffff0000u); }
; __device__ __forceinline__ float sq4(f32x4 v) { return (v[0] * v[0] + v[1] * v[1]) + (v[2] * v[2] + v[3] * v[3]); }
; __device__ __forceinline__ float sigmoidf_(float x) { return __builtin_amdgcn_rcpf(1.0f + __builtin_amdgcn_exp2f(-LOG2E * x)); }
;     __device__ __forceinline__ void operator()(const f32x4 (&acc)[2][2][4][2], const Unit& u, int wr, int wc, int fr, int fq) const {
;     ...
;                 for (int bj = 0; bj < 2; ++bj) {
;                     const u32x4 zz = zpre[m][bj];
;                     const f32x4 a = acc[ai][bj][m][0], c = acc[ai][bj][m][1];
;                     f32x4 o0, o1;
;                     o0[0] = bf_lo(zz.x) * sigmoidf_(a[0]); o0[1] = bf_hi(zz.x) * sigmoidf_(a[1]); o0[2] = bf_lo(zz.y) * sigmoidf_(a[2]); o0[3] = bf_hi(zz.y) * sigmoidf_(a[3]);
;                     o1[0] = bf_lo(zz.z) * sigmoidf_(c[0]); o1[1] = bf_hi(zz.z) * sigmoidf_(c[1]); o1[2] = bf_lo(zz.w) * sigmoidf_(c[2]); o1[3] = bf_hi(zz.w) * sigmoidf_(c[3]);
;                     ss += sq4(o0) + sq4(o1);
;                     o0 = o0 * gv[bj][0]; o1 = o1 * gv[bj][1];
;                     u32x4 w; w.x = cvt_pk_bf16(o0[0], o0[1]); w.y = cvt_pk_bf16(o0[2], o0[3]); w.z = cvt_pk_bf16(o1[0], o1[1]); w.w = cvt_pk_bf16(o1[2], o1[3]);
;                     *(u32x4*)(MIX + (size_t)row * DM + AW + col0 + 128 * bj) = w;
;                 }
;                 ss += __shfl_xor(ss, 16); ss += __shfl_xor(ss, 32);
;                 if (fq == 0) stats[(size_t)row * 8 + u.pn * 4 + wc] = ss;
	global_store_dwordx4 v[124:125], v[120:123], off offset:1024
	v_rcp_f32_e32 v116, v116
	v_rcp_f32_e32 v117, v117
	v_add_f32_e32 v118, 1.0, v118
	v_add_f32_e32 v119, 1.0, v119
	v_exp_f32_e32 v122, v112
	v_mul_f32_e32 v112, 0xbfb8aa3b, v113
	v_rcp_f32_e32 v118, v118
	v_rcp_f32_e32 v119, v119
	v_exp_f32_e32 v123, v112
	v_mul_f32_e32 v114, 0xbfb8aa3b, v114
	v_mul_f32_e32 v115, 0xbfb8aa3b, v115
	v_exp_f32_e32 v114, v114
	v_exp_f32_e32 v115, v115
	v_lshlrev_b32_e32 v120, 16, v152
	v_and_b32_e32 v121, 0xffff0000, v152
	v_pk_mul_f32 v[116:117], v[116:117], v[120:121]
	v_lshlrev_b32_e32 v120, 16, v153
	v_and_b32_e32 v121, 0xffff0000, v153
	v_pk_mul_f32 v[112:113], v[118:119], v[120:121]
	v_add_f32_e32 v118, 1.0, v122
	v_add_f32_e32 v119, 1.0, v123
	v_rcp_f32_e32 v118, v118
	v_rcp_f32_e32 v119, v119
	v_add_f32_e32 v114, 1.0, v114
	v_add_f32_e32 v115, 1.0, v115
	v_rcp_f32_e32 v114, v114
	v_rcp_f32_e32 v115, v115
	v_lshlrev_b32_e32 v120, 16, v154
	v_and_b32_e32 v121, 0xffff0000, v154
	v_pk_mul_f32 v[118:119], v[118:119], v[120:121]
	v_lshlrev_b32_e32 v120, 16, v155
	v_and_b32_e32 v121, 0xffff0000, v155
	v_pk_mul_f32 v[114:115], v[114:115], v[120:121]
	v_pk_mul_f32 v[120:121], v[116:117], v[116:117]
	v_pk_mul_f32 v[122:123], v[112:113], v[112:113]
	v_pk_mul_f32 v[134:135], v[128:129], v[128:129]
	v_add_f32_e32 v122, v122, v123
	v_add_f32_e32 v120, v120, v121
	v_pk_mul_f32 v[126:127], v[118:119], v[118:119]
	v_pk_mul_f32 v[128:129], v[114:115], v[114:115]
	v_add_f32_e32 v120, v120, v122
	v_add_f32_e32 v121, v156, v157
	v_add_f32_e32 v122, v134, v135
	v_add_f32_e32 v128, v128, v129
	v_add_f32_e32 v126, v126, v127
	v_add_f32_e32 v121, v122, v121
	v_add_f32_e32 v122, v132, v133
	v_add_f32_e32 v123, v130, v131
	v_add_f32_e32 v126, v126, v128
	v_add_f32_e32 v122, v123, v122
	v_add_f32_e32 v120, v120, v126
	v_add_f32_e32 v121, v122, v121
	v_add_f32_e32 v126, v121, v120
	ds_bpermute_b32 v127, v187, v126
	v_pk_mul_f32 v[120:121], v[66:67], v[112:113]
	v_pk_mul_f32 v[112:113], v[64:65], v[116:117]
	v_pk_mul_f32 v[122:123], v[62:63], v[114:115]
	v_cvt_pk_bf16_f32 v114, v112, v113
	s_waitcnt lgkmcnt(0)
	v_add_f32_e32 v112, v126, v127
	ds_bpermute_b32 v113, v186, v112
	v_pk_mul_f32 v[116:117], v[60:61], v[118:119]
	v_cvt_pk_bf16_f32 v115, v120, v121
	v_cvt_pk_bf16_f32 v116, v116, v117
	v_cvt_pk_bf16_f32 v117, v122, v123
	ds_bpermute_b32 v114, v226, v114
	ds_bpermute_b32 v115, v226, v115
	ds_bpermute_b32 v116, v226, v116
	ds_bpermute_b32 v117, v226, v117
	s_waitcnt lgkmcnt(0)
	global_store_dwordx4 v[124:125], v[114:117], off offset:1280
	s_and_saveexec_b64 s[44:45], vcc
	s_movk_i32 s84, 0x7dff
	s_cbranch_execz .LBB0_395
	v_lshlrev_b64 v[114:115], 5, v[180:181]
	v_lshl_add_u64 v[114:115], s[22:23], 0, v[114:115]
	v_lshl_add_u64 v[114:115], s[92:93], 2, v[114:115]
	s_lshl_b32 s42, s63, 2
	s_mov_b32 s43, s93
	v_lshl_add_u64 v[114:115], v[114:115], 0, s[42:43]
	s_waitcnt lgkmcnt(0)
	v_add_f32_e32 v112, v112, v113
	global_store_dword v[114:115], v112, off
.LBB0_395:
	s_or_b64 exec, exec, s[44:45]
	v_mul_f32_e32 v108, 0xbfb8aa3b, v108
	v_exp_f32_e32 v112, v108
	v_mul_f32_e32 v108, 0xbfb8aa3b, v109
	s_waitcnt lgkmcnt(0)
	v_exp_f32_e32 v113, v108
	v_mul_f32_e32 v110, 0xbfb8aa3b, v110
	v_add_f32_e32 v112, 1.0, v112
	v_exp_f32_e32 v116, v110
	v_add_f32_e32 v113, 1.0, v113
	v_mul_f32_e32 v110, 0xbfb8aa3b, v111
	v_rcp_f32_e32 v112, v112
	v_rcp_f32_e32 v113, v113
	v_exp_f32_e32 v117, v110
	v_lshlrev_b32_e32 v114, 16, v148
	v_and_b32_e32 v115, 0xffff0000, v148
	v_mul_f32_e32 v104, 0xbfb8aa3b, v104
	v_pk_mul_f32 v[110:111], v[112:113], v[114:115]
	v_add_f32_e32 v112, 1.0, v116
	v_add_f32_e32 v113, 1.0, v117
	v_exp_f32_e32 v116, v104
	v_mul_f32_e32 v104, 0xbfb8aa3b, v105
	v_rcp_f32_e32 v112, v112
	v_rcp_f32_e32 v113, v113
	v_exp_f32_e32 v117, v104
	v_mul_f32_e32 v106, 0xbfb8aa3b, v106
	v_mul_f32_e32 v107, 0xbfb8aa3b, v107
	v_exp_f32_e32 v106, v106
	v_exp_f32_e32 v107, v107
	v_lshlrev_b32_e32 v114, 16, v149
	v_and_b32_e32 v115, 0xffff0000, v149
	v_pk_mul_f32 v[104:105], v[112:113], v[114:115]
	v_add_f32_e32 v112, 1.0, v116
	v_add_f32_e32 v113, 1.0, v117
	v_rcp_f32_e32 v112, v112
	v_rcp_f32_e32 v113, v113
	v_add_f32_e32 v106, 1.0, v106
	v_add_f32_e32 v107, 1.0, v107
	v_rcp_f32_e32 v106, v106
	v_rcp_f32_e32 v107, v107
	v_mul_f32_e32 v100, 0xbfb8aa3b, v100
	v_mul_f32_e32 v101, 0xbfb8aa3b, v101
	v_lshlrev_b32_e32 v114, 16, v150
	v_and_b32_e32 v115, 0xffff0000, v150
	v_exp_f32_e32 v100, v100
	v_exp_f32_e32 v101, v101
	v_mul_f32_e32 v102, 0xbfb8aa3b, v102
	v_mul_f32_e32 v103, 0xbfb8aa3b, v103
	v_pk_mul_f32 v[112:113], v[112:113], v[114:115]
	v_lshlrev_b32_e32 v114, 16, v151
	v_and_b32_e32 v115, 0xffff0000, v151
	v_exp_f32_e32 v102, v102
	v_exp_f32_e32 v103, v103
	v_lshlrev_b64 v[108:109], 11, v[178:179]
	v_pk_mul_f32 v[106:107], v[106:107], v[114:115]
	v_pk_mul_f32 v[114:115], v[110:111], v[110:111]
	v_pk_mul_f32 v[116:117], v[104:105], v[104:105]
	v_pk_mul_f32 v[120:121], v[106:107], v[106:107]
	v_pk_mul_f32 v[122:123], v[78:79], v[104:105]
	v_pk_mul_f32 v[104:105], v[76:77], v[110:111]
	v_pk_mul_f32 v[110:111], v[74:75], v[106:107]
	v_pk_mul_f32 v[106:107], v[72:73], v[112:113]
	v_lshl_add_u64 v[108:109], s[38:39], 0, v[108:109]
	v_cvt_pk_bf16_f32 v104, v104, v105
	v_cvt_pk_bf16_f32 v105, v122, v123
	v_cvt_pk_bf16_f32 v106, v106, v107
	v_cvt_pk_bf16_f32 v107, v110, v111
	v_lshl_add_u64 v[108:109], v[170:171], 1, v[108:109]
	v_add_f32_e32 v100, 1.0, v100
	v_add_f32_e32 v101, 1.0, v101
	v_mul_f32_e32 v96, 0xbfb8aa3b, v96
	v_lshl_add_u64 v[108:109], v[224:225], 0, v[108:109]
	ds_bpermute_b32 v104, v226, v104
	ds_bpermute_b32 v105, v226, v105
	ds_bpermute_b32 v106, v226, v106
	ds_bpermute_b32 v107, v226, v107
	s_waitcnt lgkmcnt(0)
; __device__ __forceinline__ unsigned cvt_pk_bf16(float lo, float hi) { const cvt_f32x2_t v = {lo, hi}; const cvt_bf16x2_t b = __builtin_convertvector(v, cvt_bf16x2_t); return __builtin_bit_cast(unsigned, b); }
; __device__ __forceinline__ float bf_lo(unsigned u) { return __uint_as_float(u << 16); }
; __device__ __forceinline__ float bf_hi(unsigned u) { return __uint_as_float(u & 0xffff0000u); }
; __device__ __forceinline__ float sq4(f32x4 v) { return (v[0] * v[0] + v[1] * v[1]) + (v[2] * v[2] + v[3] * v[3]); }
; __device__ __forceinline__ float sigmoidf_(float x) { return __builtin_amdgcn_rcpf(1.0f + __builtin_amdgcn_exp2f(-LOG2E * x)); }
;     __device__ __forceinline__ void operator()(const f32x4 (&acc)[2][2][4][2], const Unit& u, int wr, int wc, int fr, int fq) const {
;     ...
;                 for (int bj = 0; bj < 2; ++bj) {
;                     const u32x4 zz = zpre[m][bj];
;                     const f32x4 a = acc[ai][bj][m][0], c = acc[ai][bj][m][1];
;                     f32x4 o0, o1;
;                     o0[0] = bf_lo(zz.x) * sigmoidf_(a[0]); o0[1] = bf_hi(zz.x) * sigmoidf_(a[1]); o0[2] = bf_lo(zz.y) * sigmoidf_(a[2]); o0[3] = bf_hi(zz.y) * sigmoidf_(a[3]);
;                     o1[0] = bf_lo(zz.z) * sigmoidf_(c[0]); o1[1] = bf_hi(zz.z) * sigmoidf_(c[1]); o1[2] = bf_lo(zz.w) * sigmoidf_(c[2]); o1[3] = bf_hi(zz.w) * sigmoidf_(c[3]);
;                     ss += sq4(o0) + sq4(o1);
;                     o0 = o0 * gv[bj][0]; o1 = o1 * gv[bj][1];
;                     u32x4 w; w.x = cvt_pk_bf16(o0[0], o0[1]); w.y = cvt_pk_bf16(o0[2], o0[3]); w.z = cvt_pk_bf16(o1[0], o1[1]); w.w = cvt_pk_bf16(o1[2], o1[3]);
;                     *(u32x4*)(MIX + (size_t)row * DM + AW + col0 + 128 * bj) = w;
;                 }
;                 ss += __shfl_xor(ss, 16); ss += __shfl_xor(ss, 32);
;                 if (fq == 0) stats[(size_t)row * 8 + u.pn * 4 + wc] = ss;
	global_store_dwordx4 v[108:109], v[104:107], off offset:1024
	v_rcp_f32_e32 v100, v100
	v_rcp_f32_e32 v101, v101
	v_add_f32_e32 v102, 1.0, v102
	v_add_f32_e32 v103, 1.0, v103
	v_exp_f32_e32 v106, v96
	v_mul_f32_e32 v96, 0xbfb8aa3b, v97
	v_rcp_f32_e32 v102, v102
	v_rcp_f32_e32 v103, v103
	v_exp_f32_e32 v107, v96
	v_mul_f32_e32 v98, 0xbfb8aa3b, v98
	v_mul_f32_e32 v99, 0xbfb8aa3b, v99
	v_exp_f32_e32 v98, v98
	v_exp_f32_e32 v99, v99
	v_lshlrev_b32_e32 v104, 16, v144
	v_and_b32_e32 v105, 0xffff0000, v144
	v_pk_mul_f32 v[100:101], v[100:101], v[104:105]
	v_lshlrev_b32_e32 v104, 16, v145
	v_and_b32_e32 v105, 0xffff0000, v145
	v_pk_mul_f32 v[96:97], v[102:103], v[104:105]
	v_add_f32_e32 v102, 1.0, v106
	v_add_f32_e32 v103, 1.0, v107
	v_rcp_f32_e32 v102, v102
	v_rcp_f32_e32 v103, v103
	v_add_f32_e32 v98, 1.0, v98
	v_add_f32_e32 v99, 1.0, v99
	v_rcp_f32_e32 v98, v98
	v_rcp_f32_e32 v99, v99
	v_lshlrev_b32_e32 v104, 16, v146
	v_and_b32_e32 v105, 0xffff0000, v146
	v_pk_mul_f32 v[102:103], v[102:103], v[104:105]
	v_lshlrev_b32_e32 v104, 16, v147
	v_and_b32_e32 v105, 0xffff0000, v147
	v_pk_mul_f32 v[98:99], v[98:99], v[104:105]
	v_pk_mul_f32 v[104:105], v[100:101], v[100:101]
	v_pk_mul_f32 v[106:107], v[96:97], v[96:97]
	v_pk_mul_f32 v[118:119], v[112:113], v[112:113]
	v_add_f32_e32 v106, v106, v107
	v_add_f32_e32 v104, v104, v105
	v_pk_mul_f32 v[110:111], v[102:103], v[102:103]
	v_pk_mul_f32 v[112:113], v[98:99], v[98:99]
	v_add_f32_e32 v104, v104, v106
	v_add_f32_e32 v105, v120, v121
	v_add_f32_e32 v106, v118, v119
	v_add_f32_e32 v112, v112, v113
	v_add_f32_e32 v110, v110, v111
	v_add_f32_e32 v105, v106, v105
	v_add_f32_e32 v106, v116, v117
	v_add_f32_e32 v107, v114, v115
	v_add_f32_e32 v110, v110, v112
	v_add_f32_e32 v106, v107, v106
	v_add_f32_e32 v104, v104, v110
	v_add_f32_e32 v105, v106, v105
	v_add_f32_e32 v110, v105, v104
	ds_bpermute_b32 v111, v187, v110
	v_pk_mul_f32 v[104:105], v[66:67], v[96:97]
	v_pk_mul_f32 v[96:97], v[64:65], v[100:101]
	v_pk_mul_f32 v[106:107], v[62:63], v[98:99]
	v_cvt_pk_bf16_f32 v98, v96, v97
	s_waitcnt lgkmcnt(0)
	v_add_f32_e32 v96, v110, v111
	ds_bpermute_b32 v97, v186, v96
	v_pk_mul_f32 v[100:101], v[60:61], v[102:103]
	v_cvt_pk_bf16_f32 v99, v104, v105
	v_cvt_pk_bf16_f32 v100, v100, v101
	v_cvt_pk_bf16_f32 v101, v106, v107
	ds_bpermute_b32 v98, v226, v98
	ds_bpermute_b32 v99, v226, v99
	ds_bpermute_b32 v100, v226, v100
	ds_bpermute_b32 v101, v226, v101
	s_waitcnt lgkmcnt(0)
	global_store_dwordx4 v[108:109], v[98:101], off offset:1280
	s_and_saveexec_b64 s[44:45], vcc
	s_cbranch_execz .LBB0_397
	v_lshlrev_b64 v[98:99], 5, v[178:179]
	v_lshl_add_u64 v[98:99], s[22:23], 0, v[98:99]
	v_lshl_add_u64 v[98:99], s[92:93], 2, v[98:99]
	s_lshl_b32 s42, s63, 2
	s_mov_b32 s43, s93
	v_lshl_add_u64 v[98:99], v[98:99], 0, s[42:43]
	s_waitcnt lgkmcnt(0)
	v_add_f32_e32 v96, v96, v97
	global_store_dword v[98:99], v96, off
.LBB0_397:
	s_or_b64 exec, exec, s[44:45]
	v_mul_f32_e32 v92, 0xbfb8aa3b, v92
	v_exp_f32_e32 v96, v92
	v_mul_f32_e32 v92, 0xbfb8aa3b, v93
	s_waitcnt lgkmcnt(0)
	v_exp_f32_e32 v97, v92
	v_mul_f32_e32 v94, 0xbfb8aa3b, v94
	v_add_f32_e32 v96, 1.0, v96
	v_exp_f32_e32 v100, v94
	v_add_f32_e32 v97, 1.0, v97
	v_mul_f32_e32 v94, 0xbfb8aa3b, v95
	v_rcp_f32_e32 v96, v96
	v_rcp_f32_e32 v97, v97
	v_exp_f32_e32 v101, v94
	v_lshlrev_b32_e32 v98, 16, v140
	v_and_b32_e32 v99, 0xffff0000, v140
	v_mul_f32_e32 v88, 0xbfb8aa3b, v88
	v_pk_mul_f32 v[94:95], v[96:97], v[98:99]
	v_add_f32_e32 v96, 1.0, v100
	v_add_f32_e32 v97, 1.0, v101
	v_exp_f32_e32 v100, v88
	v_mul_f32_e32 v88, 0xbfb8aa3b, v89
	v_rcp_f32_e32 v96, v96
	v_rcp_f32_e32 v97, v97
	v_exp_f32_e32 v101, v88
	v_mul_f32_e32 v90, 0xbfb8aa3b, v90
	v_mul_f32_e32 v91, 0xbfb8aa3b, v91
	v_exp_f32_e32 v90, v90
	v_exp_f32_e32 v91, v91
	v_lshlrev_b32_e32 v98, 16, v141
	v_and_b32_e32 v99, 0xffff0000, v141
	v_pk_mul_f32 v[88:89], v[96:97], v[98:99]
	v_add_f32_e32 v96, 1.0, v100
	v_add_f32_e32 v97, 1.0, v101
	v_rcp_f32_e32 v96, v96
	v_rcp_f32_e32 v97, v97
	v_add_f32_e32 v90, 1.0, v90
	v_add_f32_e32 v91, 1.0, v91
	v_rcp_f32_e32 v90, v90
	v_rcp_f32_e32 v91, v91
	v_mul_f32_e32 v84, 0xbfb8aa3b, v84
	v_mul_f32_e32 v85, 0xbfb8aa3b, v85
	v_lshlrev_b32_e32 v98, 16, v142
	v_and_b32_e32 v99, 0xffff0000, v142
	v_exp_f32_e32 v84, v84
	v_exp_f32_e32 v85, v85
	v_mul_f32_e32 v86, 0xbfb8aa3b, v86
	v_mul_f32_e32 v87, 0xbfb8aa3b, v87
	v_pk_mul_f32 v[96:97], v[96:97], v[98:99]
	v_lshlrev_b32_e32 v98, 16, v143
	v_and_b32_e32 v99, 0xffff0000, v143
	v_exp_f32_e32 v86, v86
	v_exp_f32_e32 v87, v87
	v_lshlrev_b64 v[92:93], 11, v[176:177]
	v_pk_mul_f32 v[90:91], v[90:91], v[98:99]
	v_pk_mul_f32 v[98:99], v[94:95], v[94:95]
	v_pk_mul_f32 v[100:101], v[88:89], v[88:89]
	v_pk_mul_f32 v[104:105], v[90:91], v[90:91]
	v_pk_mul_f32 v[106:107], v[78:79], v[88:89]
	v_pk_mul_f32 v[88:89], v[76:77], v[94:95]
	v_pk_mul_f32 v[94:95], v[74:75], v[90:91]
	v_pk_mul_f32 v[90:91], v[72:73], v[96:97]
	v_lshl_add_u64 v[92:93], s[38:39], 0, v[92:93]
	v_cvt_pk_bf16_f32 v88, v88, v89
	v_cvt_pk_bf16_f32 v89, v106, v107
	v_cvt_pk_bf16_f32 v90, v90, v91
	v_cvt_pk_bf16_f32 v91, v94, v95
	v_lshl_add_u64 v[92:93], v[170:171], 1, v[92:93]
	v_add_f32_e32 v84, 1.0, v84
	v_add_f32_e32 v85, 1.0, v85
	v_mul_f32_e32 v80, 0xbfb8aa3b, v80
	v_lshl_add_u64 v[92:93], v[224:225], 0, v[92:93]
	ds_bpermute_b32 v88, v226, v88
	ds_bpermute_b32 v89, v226, v89
	ds_bpermute_b32 v90, v226, v90
	ds_bpermute_b32 v91, v226, v91
	s_waitcnt lgkmcnt(0)
; __device__ __forceinline__ unsigned cvt_pk_bf16(float lo, float hi) { const cvt_f32x2_t v = {lo, hi}; const cvt_bf16x2_t b = __builtin_convertvector(v, cvt_bf16x2_t); return __builtin_bit_cast(unsigned, b); }
; __device__ __forceinline__ float bf_lo(unsigned u) { return __uint_as_float(u << 16); }
; __device__ __forceinline__ float bf_hi(unsigned u) { return __uint_as_float(u & 0xffff0000u); }
; __device__ __forceinline__ float sq4(f32x4 v) { return (v[0] * v[0] + v[1] * v[1]) + (v[2] * v[2] + v[3] * v[3]); }
; __device__ __forceinline__ float sigmoidf_(float x) { return __builtin_amdgcn_rcpf(1.0f + __builtin_amdgcn_exp2f(-LOG2E * x)); }
;     __device__ __forceinline__ void operator()(const f32x4 (&acc)[2][2][4][2], const Unit& u, int wr, int wc, int fr, int fq) const {
;     ...
;                 for (int bj = 0; bj < 2; ++bj) zpre[m][bj] = *(const u32x4*)(Z + (size_t)(u.pm * 256 + ai * 128 + wr * 64 + m * 16 + fr) * SW + col0 + 128 * bj);
;     ...
;                 for (int bj = 0; bj < 2; ++bj) {
;                     const u32x4 zz = zpre[m][bj];
;                     const f32x4 a = acc[ai][bj][m][0], c = acc[ai][bj][m][1];
;                     f32x4 o0, o1;
;                     o0[0] = bf_lo(zz.x) * sigmoidf_(a[0]); o0[1] = bf_hi(zz.x) * sigmoidf_(a[1]); o0[2] = bf_lo(zz.y) * sigmoidf_(a[2]); o0[3] = bf_hi(zz.y) * sigmoidf_(a[3]);
;                     o1[0] = bf_lo(zz.z) * sigmoidf_(c[0]); o1[1] = bf_hi(zz.z) * sigmoidf_(c[1]); o1[2] = bf_lo(zz.w) * sigmoidf_(c[2]); o1[3] = bf_hi(zz.w) * sigmoidf_(c[3]);
;                     ss += sq4(o0) + sq4(o1);
;                     o0 = o0 * gv[bj][0]; o1 = o1 * gv[bj][1];
;                     u32x4 w; w.x = cvt_pk_bf16(o0[0], o0[1]); w.y = cvt_pk_bf16(o0[2], o0[3]); w.z = cvt_pk_bf16(o1[0], o1[1]); w.w = cvt_pk_bf16(o1[2], o1[3]);
;                     *(u32x4*)(MIX + (size_t)row * DM + AW + col0 + 128 * bj) = w;
;                 }
;                 ss += __shfl_xor(ss, 16); ss += __shfl_xor(ss, 32);
;                 if (fq == 0) stats[(size_t)row * 8 + u.pn * 4 + wc] = ss;
	global_store_dwordx4 v[92:93], v[88:91], off offset:1024
	v_rcp_f32_e32 v84, v84
	v_rcp_f32_e32 v85, v85
	v_add_f32_e32 v86, 1.0, v86
	v_add_f32_e32 v87, 1.0, v87
	v_exp_f32_e32 v90, v80
	v_mul_f32_e32 v80, 0xbfb8aa3b, v81
	v_rcp_f32_e32 v86, v86
	v_rcp_f32_e32 v87, v87
	v_exp_f32_e32 v91, v80
	v_mul_f32_e32 v82, 0xbfb8aa3b, v82
	v_mul_f32_e32 v83, 0xbfb8aa3b, v83
	v_exp_f32_e32 v82, v82
	v_exp_f32_e32 v83, v83
	v_lshlrev_b32_e32 v88, 16, v136
	v_and_b32_e32 v89, 0xffff0000, v136
	v_pk_mul_f32 v[84:85], v[84:85], v[88:89]
	v_lshlrev_b32_e32 v88, 16, v137
	v_and_b32_e32 v89, 0xffff0000, v137
	v_pk_mul_f32 v[80:81], v[86:87], v[88:89]
	v_add_f32_e32 v86, 1.0, v90
	v_add_f32_e32 v87, 1.0, v91
	v_rcp_f32_e32 v86, v86
	v_rcp_f32_e32 v87, v87
	v_add_f32_e32 v82, 1.0, v82
	v_add_f32_e32 v83, 1.0, v83
	v_rcp_f32_e32 v82, v82
	v_rcp_f32_e32 v83, v83
	v_lshlrev_b32_e32 v88, 16, v138
	v_and_b32_e32 v89, 0xffff0000, v138
	v_pk_mul_f32 v[86:87], v[86:87], v[88:89]
	v_lshlrev_b32_e32 v88, 16, v139
	v_and_b32_e32 v89, 0xffff0000, v139
	v_pk_mul_f32 v[82:83], v[82:83], v[88:89]
	v_pk_mul_f32 v[88:89], v[84:85], v[84:85]
	v_pk_mul_f32 v[90:91], v[80:81], v[80:81]
	v_pk_mul_f32 v[102:103], v[96:97], v[96:97]
	v_add_f32_e32 v90, v90, v91
	v_add_f32_e32 v88, v88, v89
	v_pk_mul_f32 v[94:95], v[86:87], v[86:87]
	v_pk_mul_f32 v[96:97], v[82:83], v[82:83]
	v_add_f32_e32 v88, v88, v90
	v_add_f32_e32 v89, v104, v105
	v_add_f32_e32 v90, v102, v103
	v_add_f32_e32 v96, v96, v97
	v_add_f32_e32 v94, v94, v95
	v_add_f32_e32 v89, v90, v89
	v_add_f32_e32 v90, v100, v101
	v_add_f32_e32 v91, v98, v99
	v_add_f32_e32 v94, v94, v96
	v_add_f32_e32 v90, v91, v90
	v_add_f32_e32 v88, v88, v94
	v_add_f32_e32 v89, v90, v89
	v_add_f32_e32 v94, v89, v88
	ds_bpermute_b32 v95, v187, v94
	v_pk_mul_f32 v[88:89], v[66:67], v[80:81]
	v_pk_mul_f32 v[80:81], v[64:65], v[84:85]
	v_pk_mul_f32 v[90:91], v[62:63], v[82:83]
	v_cvt_pk_bf16_f32 v82, v80, v81
	s_waitcnt lgkmcnt(0)
	v_add_f32_e32 v80, v94, v95
	ds_bpermute_b32 v81, v186, v80
	v_pk_mul_f32 v[84:85], v[60:61], v[86:87]
	v_cvt_pk_bf16_f32 v83, v88, v89
	v_cvt_pk_bf16_f32 v84, v84, v85
	v_cvt_pk_bf16_f32 v85, v90, v91
	ds_bpermute_b32 v82, v226, v82
	ds_bpermute_b32 v83, v226, v83
	ds_bpermute_b32 v84, v226, v84
	ds_bpermute_b32 v85, v226, v85
	s_waitcnt lgkmcnt(0)
	global_store_dwordx4 v[92:93], v[82:85], off offset:1280
	s_and_saveexec_b64 s[44:45], vcc
	s_cbranch_execz .LBB0_399
	v_lshlrev_b64 v[82:83], 5, v[176:177]
	v_lshl_add_u64 v[82:83], s[22:23], 0, v[82:83]
	v_lshl_add_u64 v[82:83], s[92:93], 2, v[82:83]
	s_lshl_b32 s42, s63, 2
	s_mov_b32 s43, s93
	v_lshl_add_u64 v[82:83], v[82:83], 0, s[42:43]
	s_waitcnt lgkmcnt(0)
	v_add_f32_e32 v80, v80, v81
	global_store_dword v[82:83], v80, off
.LBB0_399:
	s_or_b64 exec, exec, s[44:45]
	v_add_u32_e32 v102, 0x80, v174
	v_ashrrev_i32_e32 v103, 31, v102
	s_waitcnt lgkmcnt(0)
	v_lshlrev_b64 v[80:81], 10, v[102:103]
	v_lshl_add_u64 v[80:81], v[172:173], 0, v[80:81]
	global_load_dwordx4 v[104:107], v[80:81], off
	global_load_dwordx4 v[108:111], v[80:81], off offset:256
	v_add_u32_e32 v100, 0x90, v174
	v_add_u32_e32 v98, 0xa0, v174
	v_add_u32_e32 v96, 0xb0, v174
	v_mul_f32_e32 v56, 0xbfb8aa3b, v56
	v_mul_f32_e32 v57, 0xbfb8aa3b, v57
	v_mul_f32_e32 v58, 0xbfb8aa3b, v58
	v_mul_f32_e32 v59, 0xbfb8aa3b, v59
	v_mul_f32_e32 v52, 0xbfb8aa3b, v52
	v_mul_f32_e32 v53, 0xbfb8aa3b, v53
	v_ashrrev_i32_e32 v101, 31, v100
	v_ashrrev_i32_e32 v99, 31, v98
	v_ashrrev_i32_e32 v97, 31, v96
	v_mul_f32_e32 v68, 0xbfb8aa3b, v68
	v_mul_f32_e32 v69, 0xbfb8aa3b, v69
	v_exp_f32_e32 v118, v56
	v_exp_f32_e32 v119, v57
	v_exp_f32_e32 v120, v58
	v_exp_f32_e32 v121, v59
	v_exp_f32_e32 v128, v52
	v_exp_f32_e32 v129, v53
	v_lshlrev_b64 v[52:53], 10, v[100:101]
	v_lshlrev_b64 v[56:57], 10, v[98:99]
	v_lshlrev_b64 v[58:59], 10, v[96:97]
	v_mul_f32_e32 v70, 0xbfb8aa3b, v70
	v_mul_f32_e32 v71, 0xbfb8aa3b, v71
	v_exp_f32_e32 v114, v68
	v_exp_f32_e32 v115, v69
	v_lshlrev_b64 v[68:69], 11, v[102:103]
	v_lshl_add_u64 v[52:53], v[172:173], 0, v[52:53]
	v_lshl_add_u64 v[56:57], v[172:173], 0, v[56:57]
	v_lshl_add_u64 v[58:59], v[172:173], 0, v[58:59]
	v_exp_f32_e32 v116, v70
	v_exp_f32_e32 v117, v71
	v_lshl_add_u64 v[112:113], s[38:39], 0, v[68:69]
	global_load_dwordx4 v[92:95], v[52:53], off
	global_load_dwordx4 v[88:91], v[52:53], off offset:256
	global_load_dwordx4 v[84:87], v[56:57], off
	global_load_dwordx4 v[80:83], v[56:57], off offset:256
	global_load_dwordx4 v[68:71], v[58:59], off
	s_nop 0
	global_load_dwordx4 v[56:59], v[58:59], off offset:256
	v_add_f32_e32 v52, 1.0, v114
	v_add_f32_e32 v53, 1.0, v115
	v_add_f32_e32 v114, 1.0, v116
	v_add_f32_e32 v115, 1.0, v117
	v_add_f32_e32 v116, 1.0, v118
	v_add_f32_e32 v117, 1.0, v119
	v_add_f32_e32 v118, 1.0, v120
	v_add_f32_e32 v119, 1.0, v121
	v_rcp_f32_e32 v52, v52
	v_rcp_f32_e32 v53, v53
	v_rcp_f32_e32 v114, v114
	v_rcp_f32_e32 v115, v115
	v_rcp_f32_e32 v116, v116
	v_rcp_f32_e32 v117, v117
	v_rcp_f32_e32 v118, v118
	v_rcp_f32_e32 v119, v119
	v_mul_f32_e32 v54, 0xbfb8aa3b, v54
	v_mul_f32_e32 v55, 0xbfb8aa3b, v55
	v_exp_f32_e32 v54, v54
	v_exp_f32_e32 v55, v55
	v_lshl_add_u64 v[112:113], v[170:171], 1, v[112:113]
	v_mul_f32_e32 v48, 0xbfb8aa3b, v48
	v_add_f32_e32 v54, 1.0, v54
	v_add_f32_e32 v55, 1.0, v55
	v_rcp_f32_e32 v54, v54
	v_rcp_f32_e32 v55, v55
	v_mul_f32_e32 v50, 0xbfb8aa3b, v50
	v_mul_f32_e32 v51, 0xbfb8aa3b, v51
	v_exp_f32_e32 v50, v50
	v_exp_f32_e32 v51, v51
	v_add_f32_e32 v50, 1.0, v50
	v_add_f32_e32 v51, 1.0, v51
	v_rcp_f32_e32 v50, v50
	v_rcp_f32_e32 v51, v51
	s_waitcnt vmcnt(7)
; __device__ __forceinline__ unsigned cvt_pk_bf16(float lo, float hi) { const cvt_f32x2_t v = {lo, hi}; const cvt_bf16x2_t b = __builtin_convertvector(v, cvt_bf16x2_t); return __builtin_bit_cast(unsigned, b); }
; __device__ __forceinline__ float bf_lo(unsigned u) { return __uint_as_float(u << 16); }
; __device__ __forceinline__ float bf_hi(unsigned u) { return __uint_as_float(u & 0xffff0000u); }
; __device__ __forceinline__ float sq4(f32x4 v) { return (v[0] * v[0] + v[1] * v[1]) + (v[2] * v[2] + v[3] * v[3]); }
; __device__ __forceinline__ float sigmoidf_(float x) { return __builtin_amdgcn_rcpf(1.0f + __builtin_amdgcn_exp2f(-LOG2E * x)); }
;     __device__ __forceinline__ void operator()(const f32x4 (&acc)[2][2][4][2], const Unit& u, int wr, int wc, int fr, int fq) const {
;     ...
;                 for (int bj = 0; bj < 2; ++bj) {
;                     const u32x4 zz = zpre[m][bj];
;                     const f32x4 a = acc[ai][bj][m][0], c = acc[ai][bj][m][1];
;                     f32x4 o0, o1;
;                     o0[0] = bf_lo(zz.x) * sigmoidf_(a[0]); o0[1] = bf_hi(zz.x) * sigmoidf_(a[1]); o0[2] = bf_lo(zz.y) * sigmoidf_(a[2]); o0[3] = bf_hi(zz.y) * sigmoidf_(a[3]);
;                     o1[0] = bf_lo(zz.z) * sigmoidf_(c[0]); o1[1] = bf_hi(zz.z) * sigmoidf_(c[1]); o1[2] = bf_lo(zz.w) * sigmoidf_(c[2]); o1[3] = bf_hi(zz.w) * sigmoidf_(c[3]);
;                     ss += sq4(o0) + sq4(o1);
;                     o0 = o0 * gv[bj][0]; o1 = o1 * gv[bj][1];
;                     u32x4 w; w.x = cvt_pk_bf16(o0[0], o0[1]); w.y = cvt_pk_bf16(o0[2], o0[3]); w.z = cvt_pk_bf16(o1[0], o1[1]); w.w = cvt_pk_bf16(o1[2], o1[3]);
;                     *(u32x4*)(MIX + (size_t)row * DM + AW + col0 + 128 * bj) = w;
;                 }
;                 ss += __shfl_xor(ss, 16); ss += __shfl_xor(ss, 32);
;                 if (fq == 0) stats[(size_t)row * 8 + u.pn * 4 + wc] = ss;
	v_lshlrev_b32_e32 v120, 16, v104
	v_and_b32_e32 v121, 0xffff0000, v104
	v_lshlrev_b32_e32 v104, 16, v105
	v_and_b32_e32 v105, 0xffff0000, v105
	v_lshlrev_b32_e32 v122, 16, v106
	v_and_b32_e32 v123, 0xffff0000, v106
	v_lshlrev_b32_e32 v106, 16, v107
	v_and_b32_e32 v107, 0xffff0000, v107
	v_pk_mul_f32 v[52:53], v[52:53], v[120:121]
	v_pk_mul_f32 v[104:105], v[114:115], v[104:105]
	v_pk_mul_f32 v[114:115], v[116:117], v[122:123]
	v_pk_mul_f32 v[106:107], v[118:119], v[106:107]
	v_pk_mul_f32 v[116:117], v[52:53], v[52:53]
	v_pk_mul_f32 v[122:123], v[106:107], v[106:107]
	v_pk_mul_f32 v[124:125], v[78:79], v[104:105]
	v_pk_mul_f32 v[52:53], v[76:77], v[52:53]
	v_pk_mul_f32 v[126:127], v[74:75], v[106:107]
	v_pk_mul_f32 v[106:107], v[72:73], v[114:115]
	v_pk_mul_f32 v[118:119], v[104:105], v[104:105]
	v_cvt_pk_bf16_f32 v104, v52, v53
	v_cvt_pk_bf16_f32 v105, v124, v125
	v_cvt_pk_bf16_f32 v106, v106, v107
	v_cvt_pk_bf16_f32 v107, v126, v127
	v_add_f32_e32 v52, 1.0, v128
	v_add_f32_e32 v53, 1.0, v129
	v_lshl_add_u64 v[112:113], v[224:225], 0, v[112:113]
	ds_bpermute_b32 v104, v226, v104
	ds_bpermute_b32 v105, v226, v105
	ds_bpermute_b32 v106, v226, v106
	ds_bpermute_b32 v107, v226, v107
	s_waitcnt lgkmcnt(0)
	global_store_dwordx4 v[112:113], v[104:107], off offset:1024
	v_rcp_f32_e32 v52, v52
	v_rcp_f32_e32 v53, v53
	v_exp_f32_e32 v106, v48
	v_mul_f32_e32 v48, 0xbfb8aa3b, v49
	v_exp_f32_e32 v107, v48
	s_waitcnt vmcnt(7)
	v_lshlrev_b32_e32 v104, 16, v108
	v_and_b32_e32 v105, 0xffff0000, v108
	v_pk_mul_f32 v[52:53], v[52:53], v[104:105]
	v_lshlrev_b32_e32 v104, 16, v109
	v_and_b32_e32 v105, 0xffff0000, v109
	v_pk_mul_f32 v[48:49], v[54:55], v[104:105]
	v_add_f32_e32 v54, 1.0, v106
	v_add_f32_e32 v55, 1.0, v107
	v_rcp_f32_e32 v54, v54
	v_rcp_f32_e32 v55, v55
	v_lshlrev_b32_e32 v104, 16, v110
	v_and_b32_e32 v105, 0xffff0000, v110
	v_pk_mul_f32 v[106:107], v[48:49], v[48:49]
	v_pk_mul_f32 v[54:55], v[54:55], v[104:105]
	v_lshlrev_b32_e32 v104, 16, v111
	v_and_b32_e32 v105, 0xffff0000, v111
	v_pk_mul_f32 v[50:51], v[50:51], v[104:105]
	v_pk_mul_f32 v[104:105], v[52:53], v[52:53]
	v_pk_mul_f32 v[120:121], v[114:115], v[114:115]
	v_add_f32_e32 v106, v106, v107
	v_add_f32_e32 v104, v104, v105
	v_pk_mul_f32 v[108:109], v[54:55], v[54:55]
	v_pk_mul_f32 v[110:111], v[50:51], v[50:51]
	v_add_f32_e32 v104, v104, v106
	v_add_f32_e32 v105, v122, v123
	v_add_f32_e32 v106, v120, v121
	v_add_f32_e32 v110, v110, v111
	v_add_f32_e32 v108, v108, v109
	v_add_f32_e32 v105, v106, v105
	v_add_f32_e32 v106, v118, v119
	v_add_f32_e32 v107, v116, v117
	v_add_f32_e32 v108, v108, v110
	v_add_f32_e32 v106, v107, v106
	v_add_f32_e32 v104, v104, v108
	v_add_f32_e32 v105, v106, v105
	v_add_f32_e32 v108, v105, v104
	ds_bpermute_b32 v109, v187, v108
	v_pk_mul_f32 v[104:105], v[66:67], v[48:49]
	v_pk_mul_f32 v[48:49], v[64:65], v[52:53]
	v_pk_mul_f32 v[106:107], v[62:63], v[50:51]
	v_cvt_pk_bf16_f32 v50, v48, v49
	s_waitcnt lgkmcnt(0)
	v_add_f32_e32 v48, v108, v109
	ds_bpermute_b32 v49, v186, v48
	v_pk_mul_f32 v[52:53], v[60:61], v[54:55]
	v_cvt_pk_bf16_f32 v51, v104, v105
	v_cvt_pk_bf16_f32 v52, v52, v53
	v_cvt_pk_bf16_f32 v53, v106, v107
	ds_bpermute_b32 v50, v226, v50
	ds_bpermute_b32 v51, v226, v51
	ds_bpermute_b32 v52, v226, v52
	ds_bpermute_b32 v53, v226, v53
	s_waitcnt lgkmcnt(0)
	global_store_dwordx4 v[112:113], v[50:53], off offset:1280
	s_and_saveexec_b64 s[44:45], vcc
	s_cbranch_execz .LBB0_401
	v_lshlrev_b64 v[50:51], 5, v[102:103]
	v_lshl_add_u64 v[50:51], s[22:23], 0, v[50:51]
	v_lshl_add_u64 v[50:51], s[92:93], 2, v[50:51]
	s_lshl_b32 s42, s63, 2
	s_mov_b32 s43, s93
	v_lshl_add_u64 v[50:51], v[50:51], 0, s[42:43]
	s_waitcnt lgkmcnt(0)
	v_add_f32_e32 v48, v48, v49
	global_store_dword v[50:51], v48, off
.LBB0_401:
	s_or_b64 exec, exec, s[44:45]
	v_mul_f32_e32 v44, 0xbfb8aa3b, v44
	v_exp_f32_e32 v48, v44
	v_mul_f32_e32 v44, 0xbfb8aa3b, v45
	s_waitcnt lgkmcnt(0)
	v_exp_f32_e32 v49, v44
	v_mul_f32_e32 v46, 0xbfb8aa3b, v46
	v_add_f32_e32 v48, 1.0, v48
	v_exp_f32_e32 v52, v46
	v_add_f32_e32 v49, 1.0, v49
	v_mul_f32_e32 v46, 0xbfb8aa3b, v47
	v_rcp_f32_e32 v48, v48
	v_rcp_f32_e32 v49, v49
	v_exp_f32_e32 v53, v46
	s_waitcnt vmcnt(7)
	v_lshlrev_b32_e32 v50, 16, v92
	v_and_b32_e32 v51, 0xffff0000, v92
	v_mul_f32_e32 v40, 0xbfb8aa3b, v40
	v_pk_mul_f32 v[46:47], v[48:49], v[50:51]
	v_add_f32_e32 v48, 1.0, v52
	v_add_f32_e32 v49, 1.0, v53
	v_exp_f32_e32 v52, v40
	v_mul_f32_e32 v40, 0xbfb8aa3b, v41
	v_rcp_f32_e32 v48, v48
	v_rcp_f32_e32 v49, v49
	v_exp_f32_e32 v53, v40
	v_mul_f32_e32 v42, 0xbfb8aa3b, v42
	v_mul_f32_e32 v43, 0xbfb8aa3b, v43
	v_exp_f32_e32 v42, v42
	v_exp_f32_e32 v43, v43
	v_lshlrev_b32_e32 v50, 16, v93
	v_and_b32_e32 v51, 0xffff0000, v93
	v_pk_mul_f32 v[40:41], v[48:49], v[50:51]
	v_add_f32_e32 v48, 1.0, v52
	v_add_f32_e32 v49, 1.0, v53
	v_rcp_f32_e32 v48, v48
	v_rcp_f32_e32 v49, v49
	v_add_f32_e32 v42, 1.0, v42
	v_add_f32_e32 v43, 1.0, v43
	v_rcp_f32_e32 v42, v42
	v_rcp_f32_e32 v43, v43
	v_mul_f32_e32 v36, 0xbfb8aa3b, v36
	v_mul_f32_e32 v37, 0xbfb8aa3b, v37
	v_lshlrev_b32_e32 v50, 16, v94
	v_and_b32_e32 v51, 0xffff0000, v94
	v_exp_f32_e32 v36, v36
	v_exp_f32_e32 v37, v37
	v_mul_f32_e32 v38, 0xbfb8aa3b, v38
	v_mul_f32_e32 v39, 0xbfb8aa3b, v39
	v_pk_mul_f32 v[48:49], v[48:49], v[50:51]
	v_lshlrev_b32_e32 v50, 16, v95
	v_and_b32_e32 v51, 0xffff0000, v95
	v_exp_f32_e32 v38, v38
	v_exp_f32_e32 v39, v39
	v_lshlrev_b64 v[44:45], 11, v[100:101]
	v_pk_mul_f32 v[42:43], v[42:43], v[50:51]
	v_pk_mul_f32 v[50:51], v[46:47], v[46:47]
	v_pk_mul_f32 v[52:53], v[40:41], v[40:41]
	v_pk_mul_f32 v[92:93], v[42:43], v[42:43]
	v_pk_mul_f32 v[94:95], v[78:79], v[40:41]
	v_pk_mul_f32 v[40:41], v[76:77], v[46:47]
	v_pk_mul_f32 v[46:47], v[74:75], v[42:43]
	v_pk_mul_f32 v[42:43], v[72:73], v[48:49]
	v_lshl_add_u64 v[44:45], s[38:39], 0, v[44:45]
	v_cvt_pk_bf16_f32 v40, v40, v41
	v_cvt_pk_bf16_f32 v41, v94, v95
	v_cvt_pk_bf16_f32 v42, v42, v43
	v_cvt_pk_bf16_f32 v43, v46, v47
	v_lshl_add_u64 v[44:45], v[170:171], 1, v[44:45]
	v_add_f32_e32 v36, 1.0, v36
	v_add_f32_e32 v37, 1.0, v37
	v_mul_f32_e32 v32, 0xbfb8aa3b, v32
	v_lshl_add_u64 v[44:45], v[224:225], 0, v[44:45]
	ds_bpermute_b32 v40, v226, v40
	ds_bpermute_b32 v41, v226, v41
	ds_bpermute_b32 v42, v226, v42
	ds_bpermute_b32 v43, v226, v43
	s_waitcnt lgkmcnt(0)
; __device__ __forceinline__ unsigned cvt_pk_bf16(float lo, float hi) { const cvt_f32x2_t v = {lo, hi}; const cvt_bf16x2_t b = __builtin_convertvector(v, cvt_bf16x2_t); return __builtin_bit_cast(unsigned, b); }
; __device__ __forceinline__ float bf_lo(unsigned u) { return __uint_as_float(u << 16); }
; __device__ __forceinline__ float bf_hi(unsigned u) { return __uint_as_float(u & 0xffff0000u); }
; __device__ __forceinline__ float sq4(f32x4 v) { return (v[0] * v[0] + v[1] * v[1]) + (v[2] * v[2] + v[3] * v[3]); }
; __device__ __forceinline__ float sigmoidf_(float x) { return __builtin_amdgcn_rcpf(1.0f + __builtin_amdgcn_exp2f(-LOG2E * x)); }
;     __device__ __forceinline__ void operator()(const f32x4 (&acc)[2][2][4][2], const Unit& u, int wr, int wc, int fr, int fq) const {
;     ...
;                 for (int bj = 0; bj < 2; ++bj) {
;                     const u32x4 zz = zpre[m][bj];
;                     const f32x4 a = acc[ai][bj][m][0], c = acc[ai][bj][m][1];
;                     f32x4 o0, o1;
;                     o0[0] = bf_lo(zz.x) * sigmoidf_(a[0]); o0[1] = bf_hi(zz.x) * sigmoidf_(a[1]); o0[2] = bf_lo(zz.y) * sigmoidf_(a[2]); o0[3] = bf_hi(zz.y) * sigmoidf_(a[3]);
;                     o1[0] = bf_lo(zz.z) * sigmoidf_(c[0]); o1[1] = bf_hi(zz.z) * sigmoidf_(c[1]); o1[2] = bf_lo(zz.w) * sigmoidf_(c[2]); o1[3] = bf_hi(zz.w) * sigmoidf_(c[3]);
;                     ss += sq4(o0) + sq4(o1);
;                     o0 = o0 * gv[bj][0]; o1 = o1 * gv[bj][1];
;                     u32x4 w; w.x = cvt_pk_bf16(o0[0], o0[1]); w.y = cvt_pk_bf16(o0[2], o0[3]); w.z = cvt_pk_bf16(o1[0], o1[1]); w.w = cvt_pk_bf16(o1[2], o1[3]);
;                     *(u32x4*)(MIX + (size_t)row * DM + AW + col0 + 128 * bj) = w;
;                 }
;                 ss += __shfl_xor(ss, 16); ss += __shfl_xor(ss, 32);
;                 if (fq == 0) stats[(size_t)row * 8 + u.pn * 4 + wc] = ss;
	global_store_dwordx4 v[44:45], v[40:43], off offset:1024
	v_rcp_f32_e32 v36, v36
	v_rcp_f32_e32 v37, v37
	v_add_f32_e32 v38, 1.0, v38
	v_add_f32_e32 v39, 1.0, v39
	v_exp_f32_e32 v42, v32
	v_mul_f32_e32 v32, 0xbfb8aa3b, v33
	v_rcp_f32_e32 v38, v38
	v_rcp_f32_e32 v39, v39
	v_exp_f32_e32 v43, v32
	v_mul_f32_e32 v34, 0xbfb8aa3b, v34
	v_mul_f32_e32 v35, 0xbfb8aa3b, v35
	v_exp_f32_e32 v34, v34
	v_exp_f32_e32 v35, v35
	s_waitcnt vmcnt(7)
	v_lshlrev_b32_e32 v40, 16, v88
	v_and_b32_e32 v41, 0xffff0000, v88
	v_pk_mul_f32 v[36:37], v[36:37], v[40:41]
	v_lshlrev_b32_e32 v40, 16, v89
	v_and_b32_e32 v41, 0xffff0000, v89
	v_pk_mul_f32 v[32:33], v[38:39], v[40:41]
	v_add_f32_e32 v38, 1.0, v42
	v_add_f32_e32 v39, 1.0, v43
	v_rcp_f32_e32 v38, v38
	v_rcp_f32_e32 v39, v39
	v_add_f32_e32 v34, 1.0, v34
	v_add_f32_e32 v35, 1.0, v35
	v_rcp_f32_e32 v34, v34
	v_rcp_f32_e32 v35, v35
	v_lshlrev_b32_e32 v40, 16, v90
	v_and_b32_e32 v41, 0xffff0000, v90
	v_pk_mul_f32 v[38:39], v[38:39], v[40:41]
	v_lshlrev_b32_e32 v40, 16, v91
	v_and_b32_e32 v41, 0xffff0000, v91
	v_pk_mul_f32 v[34:35], v[34:35], v[40:41]
	v_pk_mul_f32 v[40:41], v[36:37], v[36:37]
	v_pk_mul_f32 v[42:43], v[32:33], v[32:33]
	v_pk_mul_f32 v[54:55], v[48:49], v[48:49]
	v_add_f32_e32 v42, v42, v43
	v_add_f32_e32 v40, v40, v41
	v_pk_mul_f32 v[46:47], v[38:39], v[38:39]
	v_pk_mul_f32 v[48:49], v[34:35], v[34:35]
	v_add_f32_e32 v40, v40, v42
	v_add_f32_e32 v41, v92, v93
	v_add_f32_e32 v42, v54, v55
	v_add_f32_e32 v48, v48, v49
	v_add_f32_e32 v46, v46, v47
	v_add_f32_e32 v41, v42, v41
	v_add_f32_e32 v42, v52, v53
	v_add_f32_e32 v43, v50, v51
	v_add_f32_e32 v46, v46, v48
	v_add_f32_e32 v42, v43, v42
	v_add_f32_e32 v40, v40, v46
	v_add_f32_e32 v41, v42, v41
	v_add_f32_e32 v46, v41, v40
	ds_bpermute_b32 v47, v187, v46
	v_pk_mul_f32 v[40:41], v[66:67], v[32:33]
	v_pk_mul_f32 v[32:33], v[64:65], v[36:37]
	v_pk_mul_f32 v[42:43], v[62:63], v[34:35]
	v_cvt_pk_bf16_f32 v34, v32, v33
	s_waitcnt lgkmcnt(0)
	v_add_f32_e32 v32, v46, v47
	ds_bpermute_b32 v33, v186, v32
	v_pk_mul_f32 v[36:37], v[60:61], v[38:39]
	v_cvt_pk_bf16_f32 v35, v40, v41
	v_cvt_pk_bf16_f32 v36, v36, v37
	v_cvt_pk_bf16_f32 v37, v42, v43
	ds_bpermute_b32 v34, v226, v34
	ds_bpermute_b32 v35, v226, v35
	ds_bpermute_b32 v36, v226, v36
	ds_bpermute_b32 v37, v226, v37
	s_waitcnt lgkmcnt(0)
	global_store_dwordx4 v[44:45], v[34:37], off offset:1280
	s_and_saveexec_b64 s[44:45], vcc
	s_cbranch_execz .LBB0_403
	v_lshlrev_b64 v[34:35], 5, v[100:101]
	v_lshl_add_u64 v[34:35], s[22:23], 0, v[34:35]
	v_lshl_add_u64 v[34:35], s[92:93], 2, v[34:35]
	s_lshl_b32 s42, s63, 2
	s_mov_b32 s43, s93
	v_lshl_add_u64 v[34:35], v[34:35], 0, s[42:43]
	s_waitcnt lgkmcnt(0)
	v_add_f32_e32 v32, v32, v33
	global_store_dword v[34:35], v32, off
.LBB0_403:
	s_or_b64 exec, exec, s[44:45]
	v_mul_f32_e32 v28, 0xbfb8aa3b, v28
	v_exp_f32_e32 v32, v28
	v_mul_f32_e32 v28, 0xbfb8aa3b, v29
	s_waitcnt lgkmcnt(0)
	v_exp_f32_e32 v33, v28
	v_mul_f32_e32 v30, 0xbfb8aa3b, v30
	v_add_f32_e32 v32, 1.0, v32
	v_exp_f32_e32 v36, v30
	v_add_f32_e32 v33, 1.0, v33
	v_mul_f32_e32 v30, 0xbfb8aa3b, v31
	v_rcp_f32_e32 v32, v32
	v_rcp_f32_e32 v33, v33
	v_exp_f32_e32 v37, v30
	s_waitcnt vmcnt(7)
	v_lshlrev_b32_e32 v34, 16, v84
	v_and_b32_e32 v35, 0xffff0000, v84
	v_mul_f32_e32 v24, 0xbfb8aa3b, v24
	v_pk_mul_f32 v[30:31], v[32:33], v[34:35]
	v_add_f32_e32 v32, 1.0, v36
	v_add_f32_e32 v33, 1.0, v37
	v_exp_f32_e32 v36, v24
	v_mul_f32_e32 v24, 0xbfb8aa3b, v25
	v_rcp_f32_e32 v32, v32
	v_rcp_f32_e32 v33, v33
	v_exp_f32_e32 v37, v24
	v_mul_f32_e32 v26, 0xbfb8aa3b, v26
	v_mul_f32_e32 v27, 0xbfb8aa3b, v27
	v_exp_f32_e32 v26, v26
	v_exp_f32_e32 v27, v27
	v_lshlrev_b32_e32 v34, 16, v85
	v_and_b32_e32 v35, 0xffff0000, v85
	v_pk_mul_f32 v[24:25], v[32:33], v[34:35]
	v_add_f32_e32 v32, 1.0, v36
	v_add_f32_e32 v33, 1.0, v37
	v_rcp_f32_e32 v32, v32
	v_rcp_f32_e32 v33, v33
	v_add_f32_e32 v26, 1.0, v26
	v_add_f32_e32 v27, 1.0, v27
	v_rcp_f32_e32 v26, v26
	v_rcp_f32_e32 v27, v27
	v_mul_f32_e32 v20, 0xbfb8aa3b, v20
	v_mul_f32_e32 v21, 0xbfb8aa3b, v21
	v_lshlrev_b32_e32 v34, 16, v86
	v_and_b32_e32 v35, 0xffff0000, v86
	v_exp_f32_e32 v20, v20
	v_exp_f32_e32 v21, v21
	v_mul_f32_e32 v22, 0xbfb8aa3b, v22
	v_mul_f32_e32 v23, 0xbfb8aa3b, v23
	v_pk_mul_f32 v[32:33], v[32:33], v[34:35]
	v_lshlrev_b32_e32 v34, 16, v87
	v_and_b32_e32 v35, 0xffff0000, v87
	v_exp_f32_e32 v22, v22
	v_exp_f32_e32 v23, v23
	v_lshlrev_b64 v[28:29], 11, v[98:99]
	v_pk_mul_f32 v[26:27], v[26:27], v[34:35]
	v_pk_mul_f32 v[34:35], v[30:31], v[30:31]
	v_pk_mul_f32 v[36:37], v[24:25], v[24:25]
	v_pk_mul_f32 v[40:41], v[26:27], v[26:27]
	v_pk_mul_f32 v[42:43], v[78:79], v[24:25]
	v_pk_mul_f32 v[24:25], v[76:77], v[30:31]
	v_pk_mul_f32 v[30:31], v[74:75], v[26:27]
	v_pk_mul_f32 v[26:27], v[72:73], v[32:33]
	v_lshl_add_u64 v[28:29], s[38:39], 0, v[28:29]
	v_cvt_pk_bf16_f32 v24, v24, v25
	v_cvt_pk_bf16_f32 v25, v42, v43
	v_cvt_pk_bf16_f32 v26, v26, v27
	v_cvt_pk_bf16_f32 v27, v30, v31
	v_lshl_add_u64 v[28:29], v[170:171], 1, v[28:29]
	v_add_f32_e32 v20, 1.0, v20
	v_add_f32_e32 v21, 1.0, v21
	v_mul_f32_e32 v16, 0xbfb8aa3b, v16
	v_lshl_add_u64 v[28:29], v[224:225], 0, v[28:29]
	ds_bpermute_b32 v24, v226, v24
	ds_bpermute_b32 v25, v226, v25
	ds_bpermute_b32 v26, v226, v26
	ds_bpermute_b32 v27, v226, v27
	s_waitcnt lgkmcnt(0)
	global_store_dwordx4 v[28:29], v[24:27], off offset:1024
	v_rcp_f32_e32 v20, v20
	v_rcp_f32_e32 v21, v21
	v_add_f32_e32 v22, 1.0, v22
	v_add_f32_e32 v23, 1.0, v23
	v_exp_f32_e32 v26, v16
	v_mul_f32_e32 v16, 0xbfb8aa3b, v17
	v_rcp_f32_e32 v22, v22
	v_rcp_f32_e32 v23, v23
	v_exp_f32_e32 v27, v16
	v_mul_f32_e32 v18, 0xbfb8aa3b, v18
	v_mul_f32_e32 v19, 0xbfb8aa3b, v19
	v_exp_f32_e32 v18, v18
	v_exp_f32_e32 v19, v19
	s_waitcnt vmcnt(7)
; __device__ __forceinline__ unsigned cvt_pk_bf16(float lo, float hi) { const cvt_f32x2_t v = {lo, hi}; const cvt_bf16x2_t b = __builtin_convertvector(v, cvt_bf16x2_t); return __builtin_bit_cast(unsigned, b); }
; __device__ __forceinline__ float bf_lo(unsigned u) { return __uint_as_float(u << 16); }
; __device__ __forceinline__ float bf_hi(unsigned u) { return __uint_as_float(u & 0xffff0000u); }
; __device__ __forceinline__ float sq4(f32x4 v) { return (v[0] * v[0] + v[1] * v[1]) + (v[2] * v[2] + v[3] * v[3]); }
; __device__ __forceinline__ float sigmoidf_(float x) { return __builtin_amdgcn_rcpf(1.0f + __builtin_amdgcn_exp2f(-LOG2E * x)); }
;     __device__ __forceinline__ void operator()(const f32x4 (&acc)[2][2][4][2], const Unit& u, int wr, int wc, int fr, int fq) const {
;     ...
;                 for (int bj = 0; bj < 2; ++bj) {
;                     const u32x4 zz = zpre[m][bj];
;                     const f32x4 a = acc[ai][bj][m][0], c = acc[ai][bj][m][1];
;                     f32x4 o0, o1;
;                     o0[0] = bf_lo(zz.x) * sigmoidf_(a[0]); o0[1] = bf_hi(zz.x) * sigmoidf_(a[1]); o0[2] = bf_lo(zz.y) * sigmoidf_(a[2]); o0[3] = bf_hi(zz.y) * sigmoidf_(a[3]);
;                     o1[0] = bf_lo(zz.z) * sigmoidf_(c[0]); o1[1] = bf_hi(zz.z) * sigmoidf_(c[1]); o1[2] = bf_lo(zz.w) * sigmoidf_(c[2]); o1[3] = bf_hi(zz.w) * sigmoidf_(c[3]);
;                     ss += sq4(o0) + sq4(o1);
;                     o0 = o0 * gv[bj][0]; o1 = o1 * gv[bj][1];
;                     u32x4 w; w.x = cvt_pk_bf16(o0[0], o0[1]); w.y = cvt_pk_bf16(o0[2], o0[3]); w.z = cvt_pk_bf16(o1[0], o1[1]); w.w = cvt_pk_bf16(o1[2], o1[3]);
;                     *(u32x4*)(MIX + (size_t)row * DM + AW + col0 + 128 * bj) = w;
;                 }
;                 ss += __shfl_xor(ss, 16); ss += __shfl_xor(ss, 32);
;                 if (fq == 0) stats[(size_t)row * 8 + u.pn * 4 + wc] = ss;
	v_lshlrev_b32_e32 v24, 16, v80
	v_and_b32_e32 v25, 0xffff0000, v80
	v_pk_mul_f32 v[20:21], v[20:21], v[24:25]
	v_lshlrev_b32_e32 v24, 16, v81
	v_and_b32_e32 v25, 0xffff0000, v81
	v_pk_mul_f32 v[16:17], v[22:23], v[24:25]
	v_add_f32_e32 v22, 1.0, v26
	v_add_f32_e32 v23, 1.0, v27
	v_rcp_f32_e32 v22, v22
	v_rcp_f32_e32 v23, v23
	v_add_f32_e32 v18, 1.0, v18
	v_add_f32_e32 v19, 1.0, v19
	v_rcp_f32_e32 v18, v18
	v_rcp_f32_e32 v19, v19
	v_lshlrev_b32_e32 v24, 16, v82
	v_and_b32_e32 v25, 0xffff0000, v82
	v_pk_mul_f32 v[22:23], v[22:23], v[24:25]
	v_lshlrev_b32_e32 v24, 16, v83
	v_and_b32_e32 v25, 0xffff0000, v83
	v_pk_mul_f32 v[18:19], v[18:19], v[24:25]
	v_pk_mul_f32 v[24:25], v[20:21], v[20:21]
	v_pk_mul_f32 v[26:27], v[16:17], v[16:17]
	v_pk_mul_f32 v[38:39], v[32:33], v[32:33]
	v_add_f32_e32 v26, v26, v27
	v_add_f32_e32 v24, v24, v25
	v_pk_mul_f32 v[30:31], v[22:23], v[22:23]
	v_pk_mul_f32 v[32:33], v[18:19], v[18:19]
	v_add_f32_e32 v24, v24, v26
	v_add_f32_e32 v25, v40, v41
	v_add_f32_e32 v26, v38, v39
	v_add_f32_e32 v32, v32, v33
	v_add_f32_e32 v30, v30, v31
	v_add_f32_e32 v25, v26, v25
	v_add_f32_e32 v26, v36, v37
	v_add_f32_e32 v27, v34, v35
	v_add_f32_e32 v30, v30, v32
	v_add_f32_e32 v26, v27, v26
	v_add_f32_e32 v24, v24, v30
	v_add_f32_e32 v25, v26, v25
	v_add_f32_e32 v30, v25, v24
	ds_bpermute_b32 v31, v187, v30
	v_pk_mul_f32 v[24:25], v[66:67], v[16:17]
	v_pk_mul_f32 v[16:17], v[64:65], v[20:21]
	v_pk_mul_f32 v[26:27], v[62:63], v[18:19]
	v_cvt_pk_bf16_f32 v18, v16, v17
	s_waitcnt lgkmcnt(0)
	v_add_f32_e32 v16, v30, v31
	ds_bpermute_b32 v17, v186, v16
	v_pk_mul_f32 v[20:21], v[60:61], v[22:23]
	v_cvt_pk_bf16_f32 v19, v24, v25
	v_cvt_pk_bf16_f32 v20, v20, v21
	v_cvt_pk_bf16_f32 v21, v26, v27
	ds_bpermute_b32 v18, v226, v18
	ds_bpermute_b32 v19, v226, v19
	ds_bpermute_b32 v20, v226, v20
	ds_bpermute_b32 v21, v226, v21
	s_waitcnt lgkmcnt(0)
	global_store_dwordx4 v[28:29], v[18:21], off offset:1280
	s_and_saveexec_b64 s[44:45], vcc
	s_cbranch_execz .LBB0_405
	v_lshlrev_b64 v[18:19], 5, v[98:99]
	v_lshl_add_u64 v[18:19], s[22:23], 0, v[18:19]
	v_lshl_add_u64 v[18:19], s[92:93], 2, v[18:19]
	s_lshl_b32 s42, s63, 2
	s_mov_b32 s43, s93
	v_lshl_add_u64 v[18:19], v[18:19], 0, s[42:43]
	s_waitcnt lgkmcnt(0)
	v_add_f32_e32 v16, v16, v17
	global_store_dword v[18:19], v16, off
; __device__ __forceinline__ unsigned cvt_pk_bf16(float lo, float hi) { const cvt_f32x2_t v = {lo, hi}; const cvt_bf16x2_t b = __builtin_convertvector(v, cvt_bf16x2_t); return __builtin_bit_cast(unsigned, b); }
; __device__ __forceinline__ float bf_lo(unsigned u) { return __uint_as_float(u << 16); }
; __device__ __forceinline__ float bf_hi(unsigned u) { return __uint_as_float(u & 0xffff0000u); }
; __device__ __forceinline__ float sq4(f32x4 v) { return (v[0] * v[0] + v[1] * v[1]) + (v[2] * v[2] + v[3] * v[3]); }
; __device__ __forceinline__ float sigmoidf_(float x) { return __builtin_amdgcn_rcpf(1.0f + __builtin_amdgcn_exp2f(-LOG2E * x)); }
;     __device__ __forceinline__ void operator()(const f32x4 (&acc)[2][2][4][2], const Unit& u, int wr, int wc, int fr, int fq) const {
;     ...
;                 for (int bj = 0; bj < 2; ++bj) {
;                     const u32x4 zz = zpre[m][bj];
;                     const f32x4 a = acc[ai][bj][m][0], c = acc[ai][bj][m][1];
;                     f32x4 o0, o1;
;                     o0[0] = bf_lo(zz.x) * sigmoidf_(a[0]); o0[1] = bf_hi(zz.x) * sigmoidf_(a[1]); o0[2] = bf_lo(zz.y) * sigmoidf_(a[2]); o0[3] = bf_hi(zz.y) * sigmoidf_(a[3]);
;                     o1[0] = bf_lo(zz.z) * sigmoidf_(c[0]); o1[1] = bf_hi(zz.z) * sigmoidf_(c[1]); o1[2] = bf_lo(zz.w) * sigmoidf_(c[2]); o1[3] = bf_hi(zz.w) * sigmoidf_(c[3]);
;                     ss += sq4(o0) + sq4(o1);
;                     o0 = o0 * gv[bj][0]; o1 = o1 * gv[bj][1];
;                     u32x4 w; w.x = cvt_pk_bf16(o0[0], o0[1]); w.y = cvt_pk_bf16(o0[2], o0[3]); w.z = cvt_pk_bf16(o1[0], o1[1]); w.w = cvt_pk_bf16(o1[2], o1[3]);
;                     *(u32x4*)(MIX + (size_t)row * DM + AW + col0 + 128 * bj) = w;
;                 }
;                 ss += __shfl_xor(ss, 16); ss += __shfl_xor(ss, 32);
;                 if (fq == 0) stats[(size_t)row * 8 + u.pn * 4 + wc] = ss;
.LBB0_405:
	s_or_b64 exec, exec, s[44:45]
	v_mul_f32_e32 v12, 0xbfb8aa3b, v12
	v_exp_f32_e32 v16, v12
	v_mul_f32_e32 v12, 0xbfb8aa3b, v13
	s_waitcnt lgkmcnt(0)
	v_exp_f32_e32 v17, v12
	v_mul_f32_e32 v14, 0xbfb8aa3b, v14
	v_add_f32_e32 v16, 1.0, v16
	v_exp_f32_e32 v20, v14
	v_add_f32_e32 v17, 1.0, v17
	v_mul_f32_e32 v14, 0xbfb8aa3b, v15
	v_rcp_f32_e32 v16, v16
	v_rcp_f32_e32 v17, v17
	v_exp_f32_e32 v21, v14
	s_waitcnt vmcnt(7)
	v_lshlrev_b32_e32 v18, 16, v68
	v_and_b32_e32 v19, 0xffff0000, v68
	v_mul_f32_e32 v8, 0xbfb8aa3b, v8
	v_pk_mul_f32 v[14:15], v[16:17], v[18:19]
	v_add_f32_e32 v16, 1.0, v20
	v_add_f32_e32 v17, 1.0, v21
	v_exp_f32_e32 v20, v8
	v_mul_f32_e32 v8, 0xbfb8aa3b, v9
	v_rcp_f32_e32 v16, v16
	v_rcp_f32_e32 v17, v17
	v_exp_f32_e32 v21, v8
	v_mul_f32_e32 v10, 0xbfb8aa3b, v10
	v_mul_f32_e32 v11, 0xbfb8aa3b, v11
	v_exp_f32_e32 v10, v10
	v_exp_f32_e32 v11, v11
	v_lshlrev_b32_e32 v18, 16, v69
	v_and_b32_e32 v19, 0xffff0000, v69
	v_pk_mul_f32 v[8:9], v[16:17], v[18:19]
	v_add_f32_e32 v16, 1.0, v20
	v_add_f32_e32 v17, 1.0, v21
	v_rcp_f32_e32 v16, v16
	v_rcp_f32_e32 v17, v17
	v_add_f32_e32 v10, 1.0, v10
	v_add_f32_e32 v11, 1.0, v11
	v_rcp_f32_e32 v10, v10
	v_rcp_f32_e32 v11, v11
	v_mul_f32_e32 v4, 0xbfb8aa3b, v4
	v_mul_f32_e32 v5, 0xbfb8aa3b, v5
	v_lshlrev_b32_e32 v18, 16, v70
	v_and_b32_e32 v19, 0xffff0000, v70
	v_exp_f32_e32 v4, v4
	v_exp_f32_e32 v5, v5
	v_mul_f32_e32 v6, 0xbfb8aa3b, v6
	v_mul_f32_e32 v7, 0xbfb8aa3b, v7
	v_pk_mul_f32 v[16:17], v[16:17], v[18:19]
	v_lshlrev_b32_e32 v18, 16, v71
	v_and_b32_e32 v19, 0xffff0000, v71
	v_exp_f32_e32 v6, v6
	v_exp_f32_e32 v7, v7
	v_lshlrev_b64 v[12:13], 11, v[96:97]
	v_pk_mul_f32 v[10:11], v[10:11], v[18:19]
	v_pk_mul_f32 v[18:19], v[14:15], v[14:15]
	v_pk_mul_f32 v[20:21], v[8:9], v[8:9]
	v_pk_mul_f32 v[24:25], v[10:11], v[10:11]
	v_pk_mul_f32 v[26:27], v[78:79], v[8:9]
	v_pk_mul_f32 v[8:9], v[76:77], v[14:15]
	v_pk_mul_f32 v[14:15], v[74:75], v[10:11]
	v_pk_mul_f32 v[10:11], v[72:73], v[16:17]
	v_lshl_add_u64 v[12:13], s[38:39], 0, v[12:13]
	v_cvt_pk_bf16_f32 v8, v8, v9
	v_cvt_pk_bf16_f32 v9, v26, v27
	v_cvt_pk_bf16_f32 v10, v10, v11
	v_cvt_pk_bf16_f32 v11, v14, v15
	v_lshl_add_u64 v[12:13], v[170:171], 1, v[12:13]
	v_add_f32_e32 v4, 1.0, v4
	v_add_f32_e32 v5, 1.0, v5
	v_mul_f32_e32 v0, 0xbfb8aa3b, v0
	v_lshl_add_u64 v[12:13], v[224:225], 0, v[12:13]
	ds_bpermute_b32 v8, v226, v8
	ds_bpermute_b32 v9, v226, v9
	ds_bpermute_b32 v10, v226, v10
	ds_bpermute_b32 v11, v226, v11
	s_waitcnt lgkmcnt(0)
	global_store_dwordx4 v[12:13], v[8:11], off offset:1024
	v_rcp_f32_e32 v4, v4
	v_rcp_f32_e32 v5, v5
	v_add_f32_e32 v6, 1.0, v6
	v_add_f32_e32 v7, 1.0, v7
	v_exp_f32_e32 v10, v0
	v_mul_f32_e32 v0, 0xbfb8aa3b, v1
	v_rcp_f32_e32 v6, v6
	v_rcp_f32_e32 v7, v7
	v_exp_f32_e32 v11, v0
	v_mul_f32_e32 v2, 0xbfb8aa3b, v2
	v_mul_f32_e32 v3, 0xbfb8aa3b, v3
	v_exp_f32_e32 v2, v2
	v_exp_f32_e32 v3, v3
	s_waitcnt vmcnt(7)
	v_lshlrev_b32_e32 v8, 16, v56
	v_and_b32_e32 v9, 0xffff0000, v56
	v_pk_mul_f32 v[4:5], v[4:5], v[8:9]
	v_lshlrev_b32_e32 v8, 16, v57
	v_and_b32_e32 v9, 0xffff0000, v57
	v_pk_mul_f32 v[0:1], v[6:7], v[8:9]
	v_add_f32_e32 v6, 1.0, v10
	v_add_f32_e32 v7, 1.0, v11
	v_rcp_f32_e32 v6, v6
	v_rcp_f32_e32 v7, v7
	v_add_f32_e32 v2, 1.0, v2
	v_add_f32_e32 v3, 1.0, v3
	v_rcp_f32_e32 v2, v2
	v_rcp_f32_e32 v3, v3
	v_lshlrev_b32_e32 v8, 16, v58
	v_and_b32_e32 v9, 0xffff0000, v58
	v_pk_mul_f32 v[6:7], v[6:7], v[8:9]
	v_lshlrev_b32_e32 v8, 16, v59
	v_and_b32_e32 v9, 0xffff0000, v59
	v_pk_mul_f32 v[2:3], v[2:3], v[8:9]
	v_pk_mul_f32 v[8:9], v[4:5], v[4:5]
	v_pk_mul_f32 v[10:11], v[0:1], v[0:1]
	v_pk_mul_f32 v[22:23], v[16:17], v[16:17]
	v_add_f32_e32 v10, v10, v11
	v_add_f32_e32 v8, v8, v9
	v_pk_mul_f32 v[14:15], v[6:7], v[6:7]
	v_pk_mul_f32 v[16:17], v[2:3], v[2:3]
	v_add_f32_e32 v8, v8, v10
	v_add_f32_e32 v9, v24, v25
	v_add_f32_e32 v10, v22, v23
	v_add_f32_e32 v16, v16, v17
	v_add_f32_e32 v14, v14, v15
	v_add_f32_e32 v9, v10, v9
	v_add_f32_e32 v10, v20, v21
	v_add_f32_e32 v11, v18, v19
	v_add_f32_e32 v14, v14, v16
	v_add_f32_e32 v10, v11, v10
	v_add_f32_e32 v8, v8, v14
	v_add_f32_e32 v9, v10, v9
	v_add_f32_e32 v14, v9, v8
	ds_bpermute_b32 v15, v187, v14
	v_pk_mul_f32 v[8:9], v[66:67], v[0:1]
	v_pk_mul_f32 v[0:1], v[64:65], v[4:5]
	v_pk_mul_f32 v[10:11], v[62:63], v[2:3]
	v_cvt_pk_bf16_f32 v2, v0, v1
	s_waitcnt lgkmcnt(0)
	v_add_f32_e32 v0, v14, v15
	ds_bpermute_b32 v1, v186, v0
	v_pk_mul_f32 v[4:5], v[60:61], v[6:7]
	v_cvt_pk_bf16_f32 v3, v8, v9
	v_cvt_pk_bf16_f32 v4, v4, v5
	v_cvt_pk_bf16_f32 v5, v10, v11
	ds_bpermute_b32 v2, v226, v2
	ds_bpermute_b32 v3, v226, v3
	ds_bpermute_b32 v4, v226, v4
	ds_bpermute_b32 v5, v226, v5
	s_waitcnt lgkmcnt(0)
	global_store_dwordx4 v[12:13], v[2:5], off offset:1280
	s_and_saveexec_b64 s[44:45], vcc
	s_cbranch_execnz .LBB0_407
	s_or_b64 exec, exec, s[44:45]
	s_andn2_b64 vcc, exec, s[48:49]
	s_mov_b64 s[44:45], -1
	s_cbranch_vccnz .LBB0_386
	s_branch .LBB0_408
